# v22 + gather epilogue processes two tokens per iteration, V accumulators initialised by pk_mul, cheaper U reduction stage
# baseline (speedup 1.0000x reference)
; #define PG_ISSUE(BUF, TAB, e0_) do { const int isrc_ = ((e0_) < 64) ? myi0 : myi1; \
;       _Pragma("unroll") for (int e = 0; e < 8; ++e) { const int idx_ = __builtin_amdgcn_readlane(isrc_, ((e0_) + e) & 63); \
;         BUF[e] = *(const u32x4*)((TAB) + (size_t)idx_ * 1024 + lane * 16); } } while (0)
; DEV void peer_gather(const Params& P, int l, int m0, const int* idxs, const float* gs) {
;     ...
;     PG_ISSUE(b0, U, 0);
; #pragma nounroll
;     for (int e0 = 0; e0 < 128; e0 += 16) {
;       PG_ISSUE(b1, U, e0 + 8);
;       PG_U8(b0, 0, e0);
;       if (e0 + 16 < 128) PG_ISSUE(b0, U, e0 + 16); else PG_ISSUE(b0, V, 0);
;       PG_U8(b1, 0, e0 + 8);
;     }
.Lpg0_uloop:
	s_and_b32 s98, s100, 15
	s_lshr_b32 s99, s100, 4
	s_add_u32 s92, s100, 1
	s_min_u32 s92, s92, 127
	s_lshr_b32 s93, s92, 4
	s_and_b32 s92, s92, 15
	s_waitcnt vmcnt(16)
	v_lshlrev_b32_e32 v64, 16, v80
	v_and_b32_e32 v65, 0xffff0000, v80
	v_lshlrev_b32_e32 v66, 16, v81
	v_and_b32_e32 v67, 0xffff0000, v81
	v_lshlrev_b32_e32 v68, 16, v82
	v_and_b32_e32 v69, 0xffff0000, v82
	v_lshlrev_b32_e32 v70, 16, v83
	v_and_b32_e32 v71, 0xffff0000, v83
	v_lshlrev_b32_e32 v72, 16, v84
	v_and_b32_e32 v73, 0xffff0000, v84
	v_lshlrev_b32_e32 v74, 16, v85
	v_and_b32_e32 v75, 0xffff0000, v85
	v_lshlrev_b32_e32 v76, 16, v86
	v_and_b32_e32 v77, 0xffff0000, v86
	v_lshlrev_b32_e32 v78, 16, v87
	v_and_b32_e32 v79, 0xffff0000, v87
	v_readfirstlane_b32 s82, v128
	v_readfirstlane_b32 s83, v129
	s_nop 4
	s_add_u32 vcc_lo, s3, s92
	s_lshl_b32 vcc_lo, vcc_lo, 11
	s_lshl_b32 vcc_hi, s93, 8
	s_add_u32 vcc_lo, vcc_lo, vcc_hi
	v_add_u32_e32 v119, vcc_lo, v236
	global_load_dwordx4 v[80:83], v119, s[82:83]
	global_load_dwordx4 v[84:87], v119, s[82:83] offset:16
	s_lshl_b32 vcc_lo, s93, 7
	v_add_u32_e32 v240, vcc_lo, v235
	s_waitcnt lgkmcnt(0)
	ds_bpermute_b32 v142, v249, v134
	ds_bpermute_b32 v143, v250, v134
	s_waitcnt vmcnt(16)
	v_cvt_pk_f32_fp8_e32 v[104:105], v0
	v_cvt_pk_f32_fp8_e32 v[108:109], v4
	v_cvt_pk_f32_fp8_sdwa v[106:107], v0 src0_sel:WORD_1
	v_cvt_pk_f32_fp8_sdwa v[110:111], v4 src0_sel:WORD_1
	v_pk_mul_f32 v[112:113], v[64:65], v[104:105]
	v_pk_mul_f32 v[114:115], v[64:65], v[108:109]
	v_pk_fma_f32 v[112:113], v[66:67], v[106:107], v[112:113]
	v_pk_fma_f32 v[114:115], v[66:67], v[110:111], v[114:115]
	v_cvt_pk_f32_fp8_e32 v[104:105], v1
	v_cvt_pk_f32_fp8_e32 v[108:109], v5
	v_cvt_pk_f32_fp8_sdwa v[106:107], v1 src0_sel:WORD_1
	v_cvt_pk_f32_fp8_sdwa v[110:111], v5 src0_sel:WORD_1
	v_pk_fma_f32 v[112:113], v[68:69], v[104:105], v[112:113]
	v_pk_fma_f32 v[114:115], v[68:69], v[108:109], v[114:115]
	v_pk_fma_f32 v[112:113], v[70:71], v[106:107], v[112:113]
	v_pk_fma_f32 v[114:115], v[70:71], v[110:111], v[114:115]
	v_cvt_pk_f32_fp8_e32 v[104:105], v2
	v_cvt_pk_f32_fp8_e32 v[108:109], v6
	v_cvt_pk_f32_fp8_sdwa v[106:107], v2 src0_sel:WORD_1
	v_cvt_pk_f32_fp8_sdwa v[110:111], v6 src0_sel:WORD_1
	v_pk_fma_f32 v[112:113], v[72:73], v[104:105], v[112:113]
	v_pk_fma_f32 v[114:115], v[72:73], v[108:109], v[114:115]
	v_pk_fma_f32 v[112:113], v[74:75], v[106:107], v[112:113]
	v_pk_fma_f32 v[114:115], v[74:75], v[110:111], v[114:115]
	v_cvt_pk_f32_fp8_e32 v[104:105], v3
	v_cvt_pk_f32_fp8_e32 v[108:109], v7
	v_cvt_pk_f32_fp8_sdwa v[106:107], v3 src0_sel:WORD_1
	v_cvt_pk_f32_fp8_sdwa v[110:111], v7 src0_sel:WORD_1
	v_pk_fma_f32 v[112:113], v[76:77], v[104:105], v[112:113]
	v_pk_fma_f32 v[114:115], v[76:77], v[108:109], v[114:115]
	s_waitcnt lgkmcnt(0)
	v_and_or_b32 v142, v142, s90, v240
	v_and_or_b32 v143, v143, s90, v240
	global_load_dwordx4 v[0:3], v142, s[80:81]
	global_load_dwordx4 v[4:7], v143, s[80:81]
	v_pk_fma_f32 v[112:113], v[78:79], v[106:107], v[112:113]
	v_pk_fma_f32 v[114:115], v[78:79], v[110:111], v[114:115]
	v_add_f32_e32 v88, v112, v113
	v_add_f32_e32 v89, v114, v115
	ds_bpermute_b32 v142, v251, v134
	ds_bpermute_b32 v143, v252, v134
	s_waitcnt vmcnt(16)
	v_cvt_pk_f32_fp8_e32 v[104:105], v8
	v_cvt_pk_f32_fp8_e32 v[108:109], v12
	v_cvt_pk_f32_fp8_sdwa v[106:107], v8 src0_sel:WORD_1
	v_cvt_pk_f32_fp8_sdwa v[110:111], v12 src0_sel:WORD_1
	v_pk_mul_f32 v[112:113], v[64:65], v[104:105]
	v_pk_mul_f32 v[114:115], v[64:65], v[108:109]
	v_pk_fma_f32 v[112:113], v[66:67], v[106:107], v[112:113]
	v_pk_fma_f32 v[114:115], v[66:67], v[110:111], v[114:115]
	v_cvt_pk_f32_fp8_e32 v[104:105], v9
	v_cvt_pk_f32_fp8_e32 v[108:109], v13
	v_cvt_pk_f32_fp8_sdwa v[106:107], v9 src0_sel:WORD_1
	v_cvt_pk_f32_fp8_sdwa v[110:111], v13 src0_sel:WORD_1
	v_pk_fma_f32 v[112:113], v[68:69], v[104:105], v[112:113]
	v_pk_fma_f32 v[114:115], v[68:69], v[108:109], v[114:115]
	v_pk_fma_f32 v[112:113], v[70:71], v[106:107], v[112:113]
	v_pk_fma_f32 v[114:115], v[70:71], v[110:111], v[114:115]
	v_cvt_pk_f32_fp8_e32 v[104:105], v10
	v_cvt_pk_f32_fp8_e32 v[108:109], v14
	v_cvt_pk_f32_fp8_sdwa v[106:107], v10 src0_sel:WORD_1
	v_cvt_pk_f32_fp8_sdwa v[110:111], v14 src0_sel:WORD_1
	v_pk_fma_f32 v[112:113], v[72:73], v[104:105], v[112:113]
	v_pk_fma_f32 v[114:115], v[72:73], v[108:109], v[114:115]
	v_pk_fma_f32 v[112:113], v[74:75], v[106:107], v[112:113]
	v_pk_fma_f32 v[114:115], v[74:75], v[110:111], v[114:115]
	v_cvt_pk_f32_fp8_e32 v[104:105], v11
	v_cvt_pk_f32_fp8_e32 v[108:109], v15
	v_cvt_pk_f32_fp8_sdwa v[106:107], v11 src0_sel:WORD_1
	v_cvt_pk_f32_fp8_sdwa v[110:111], v15 src0_sel:WORD_1
	v_pk_fma_f32 v[112:113], v[76:77], v[104:105], v[112:113]
	v_pk_fma_f32 v[114:115], v[76:77], v[108:109], v[114:115]
	s_waitcnt lgkmcnt(0)
	v_and_or_b32 v142, v142, s90, v240
	v_and_or_b32 v143, v143, s90, v240
	global_load_dwordx4 v[8:11], v142, s[80:81]
	global_load_dwordx4 v[12:15], v143, s[80:81]
	v_pk_fma_f32 v[112:113], v[78:79], v[106:107], v[112:113]
	v_pk_fma_f32 v[114:115], v[78:79], v[110:111], v[114:115]
	v_add_f32_e32 v90, v112, v113
	v_add_f32_e32 v91, v114, v115
	ds_bpermute_b32 v142, v253, v134
	ds_bpermute_b32 v143, v254, v134
	s_waitcnt vmcnt(16)
	v_cvt_pk_f32_fp8_e32 v[104:105], v16
	v_cvt_pk_f32_fp8_e32 v[108:109], v20
	v_cvt_pk_f32_fp8_sdwa v[106:107], v16 src0_sel:WORD_1
	v_cvt_pk_f32_fp8_sdwa v[110:111], v20 src0_sel:WORD_1
	v_pk_mul_f32 v[112:113], v[64:65], v[104:105]
	v_pk_mul_f32 v[114:115], v[64:65], v[108:109]
	v_pk_fma_f32 v[112:113], v[66:67], v[106:107], v[112:113]
	v_pk_fma_f32 v[114:115], v[66:67], v[110:111], v[114:115]
	v_cvt_pk_f32_fp8_e32 v[104:105], v17
	v_cvt_pk_f32_fp8_e32 v[108:109], v21
	v_cvt_pk_f32_fp8_sdwa v[106:107], v17 src0_sel:WORD_1
	v_cvt_pk_f32_fp8_sdwa v[110:111], v21 src0_sel:WORD_1
	v_pk_fma_f32 v[112:113], v[68:69], v[104:105], v[112:113]
	v_pk_fma_f32 v[114:115], v[68:69], v[108:109], v[114:115]
	v_pk_fma_f32 v[112:113], v[70:71], v[106:107], v[112:113]
	v_pk_fma_f32 v[114:115], v[70:71], v[110:111], v[114:115]
	v_cvt_pk_f32_fp8_e32 v[104:105], v18
	v_cvt_pk_f32_fp8_e32 v[108:109], v22
	v_cvt_pk_f32_fp8_sdwa v[106:107], v18 src0_sel:WORD_1
	v_cvt_pk_f32_fp8_sdwa v[110:111], v22 src0_sel:WORD_1
	v_pk_fma_f32 v[112:113], v[72:73], v[104:105], v[112:113]
	v_pk_fma_f32 v[114:115], v[72:73], v[108:109], v[114:115]
	v_pk_fma_f32 v[112:113], v[74:75], v[106:107], v[112:113]
	v_pk_fma_f32 v[114:115], v[74:75], v[110:111], v[114:115]
	v_cvt_pk_f32_fp8_e32 v[104:105], v19
	v_cvt_pk_f32_fp8_e32 v[108:109], v23
	v_cvt_pk_f32_fp8_sdwa v[106:107], v19 src0_sel:WORD_1
	v_cvt_pk_f32_fp8_sdwa v[110:111], v23 src0_sel:WORD_1
	v_pk_fma_f32 v[112:113], v[76:77], v[104:105], v[112:113]
	v_pk_fma_f32 v[114:115], v[76:77], v[108:109], v[114:115]
	s_waitcnt lgkmcnt(0)
	v_and_or_b32 v142, v142, s90, v240
	v_and_or_b32 v143, v143, s90, v240
	global_load_dwordx4 v[16:19], v142, s[80:81]
	global_load_dwordx4 v[20:23], v143, s[80:81]
	v_pk_fma_f32 v[112:113], v[78:79], v[106:107], v[112:113]
	v_pk_fma_f32 v[114:115], v[78:79], v[110:111], v[114:115]
	v_add_f32_e32 v92, v112, v113
	v_add_f32_e32 v93, v114, v115
	ds_bpermute_b32 v142, v255, v134
	ds_bpermute_b32 v143, v153, v134
	s_waitcnt vmcnt(16)
	v_cvt_pk_f32_fp8_e32 v[104:105], v24
	v_cvt_pk_f32_fp8_e32 v[108:109], v28
	v_cvt_pk_f32_fp8_sdwa v[106:107], v24 src0_sel:WORD_1
	v_cvt_pk_f32_fp8_sdwa v[110:111], v28 src0_sel:WORD_1
	v_pk_mul_f32 v[112:113], v[64:65], v[104:105]
	v_pk_mul_f32 v[114:115], v[64:65], v[108:109]
	v_pk_fma_f32 v[112:113], v[66:67], v[106:107], v[112:113]
	v_pk_fma_f32 v[114:115], v[66:67], v[110:111], v[114:115]
	v_cvt_pk_f32_fp8_e32 v[104:105], v25
	v_cvt_pk_f32_fp8_e32 v[108:109], v29
	v_cvt_pk_f32_fp8_sdwa v[106:107], v25 src0_sel:WORD_1
	v_cvt_pk_f32_fp8_sdwa v[110:111], v29 src0_sel:WORD_1
	v_pk_fma_f32 v[112:113], v[68:69], v[104:105], v[112:113]
	v_pk_fma_f32 v[114:115], v[68:69], v[108:109], v[114:115]
	v_pk_fma_f32 v[112:113], v[70:71], v[106:107], v[112:113]
	v_pk_fma_f32 v[114:115], v[70:71], v[110:111], v[114:115]
	v_cvt_pk_f32_fp8_e32 v[104:105], v26
	v_cvt_pk_f32_fp8_e32 v[108:109], v30
	v_cvt_pk_f32_fp8_sdwa v[106:107], v26 src0_sel:WORD_1
	v_cvt_pk_f32_fp8_sdwa v[110:111], v30 src0_sel:WORD_1
	v_pk_fma_f32 v[112:113], v[72:73], v[104:105], v[112:113]
	v_pk_fma_f32 v[114:115], v[72:73], v[108:109], v[114:115]
	v_pk_fma_f32 v[112:113], v[74:75], v[106:107], v[112:113]
	v_pk_fma_f32 v[114:115], v[74:75], v[110:111], v[114:115]
	v_cvt_pk_f32_fp8_e32 v[104:105], v27
	v_cvt_pk_f32_fp8_e32 v[108:109], v31
	v_cvt_pk_f32_fp8_sdwa v[106:107], v27 src0_sel:WORD_1
	v_cvt_pk_f32_fp8_sdwa v[110:111], v31 src0_sel:WORD_1
	v_pk_fma_f32 v[112:113], v[76:77], v[104:105], v[112:113]
	v_pk_fma_f32 v[114:115], v[76:77], v[108:109], v[114:115]
	s_waitcnt lgkmcnt(0)
	v_and_or_b32 v142, v142, s90, v240
	v_and_or_b32 v143, v143, s90, v240
	global_load_dwordx4 v[24:27], v142, s[80:81]
	global_load_dwordx4 v[28:31], v143, s[80:81]
	v_pk_fma_f32 v[112:113], v[78:79], v[106:107], v[112:113]
	v_pk_fma_f32 v[114:115], v[78:79], v[110:111], v[114:115]
	v_add_f32_e32 v94, v112, v113
	v_add_f32_e32 v95, v114, v115
	ds_bpermute_b32 v142, v249, v135
	ds_bpermute_b32 v143, v250, v135
	s_waitcnt vmcnt(16)
	v_cvt_pk_f32_fp8_e32 v[104:105], v32
	v_cvt_pk_f32_fp8_e32 v[108:109], v36
	v_cvt_pk_f32_fp8_sdwa v[106:107], v32 src0_sel:WORD_1
	v_cvt_pk_f32_fp8_sdwa v[110:111], v36 src0_sel:WORD_1
	v_pk_mul_f32 v[112:113], v[64:65], v[104:105]
	v_pk_mul_f32 v[114:115], v[64:65], v[108:109]
	v_pk_fma_f32 v[112:113], v[66:67], v[106:107], v[112:113]
	v_pk_fma_f32 v[114:115], v[66:67], v[110:111], v[114:115]
	v_cvt_pk_f32_fp8_e32 v[104:105], v33
	v_cvt_pk_f32_fp8_e32 v[108:109], v37
	v_cvt_pk_f32_fp8_sdwa v[106:107], v33 src0_sel:WORD_1
	v_cvt_pk_f32_fp8_sdwa v[110:111], v37 src0_sel:WORD_1
	v_pk_fma_f32 v[112:113], v[68:69], v[104:105], v[112:113]
	v_pk_fma_f32 v[114:115], v[68:69], v[108:109], v[114:115]
	v_pk_fma_f32 v[112:113], v[70:71], v[106:107], v[112:113]
	v_pk_fma_f32 v[114:115], v[70:71], v[110:111], v[114:115]
	v_cvt_pk_f32_fp8_e32 v[104:105], v34
	v_cvt_pk_f32_fp8_e32 v[108:109], v38
	v_cvt_pk_f32_fp8_sdwa v[106:107], v34 src0_sel:WORD_1
	v_cvt_pk_f32_fp8_sdwa v[110:111], v38 src0_sel:WORD_1
	v_pk_fma_f32 v[112:113], v[72:73], v[104:105], v[112:113]
	v_pk_fma_f32 v[114:115], v[72:73], v[108:109], v[114:115]
	v_pk_fma_f32 v[112:113], v[74:75], v[106:107], v[112:113]
	v_pk_fma_f32 v[114:115], v[74:75], v[110:111], v[114:115]
	v_cvt_pk_f32_fp8_e32 v[104:105], v35
	v_cvt_pk_f32_fp8_e32 v[108:109], v39
	v_cvt_pk_f32_fp8_sdwa v[106:107], v35 src0_sel:WORD_1
	v_cvt_pk_f32_fp8_sdwa v[110:111], v39 src0_sel:WORD_1
	v_pk_fma_f32 v[112:113], v[76:77], v[104:105], v[112:113]
	v_pk_fma_f32 v[114:115], v[76:77], v[108:109], v[114:115]
	s_waitcnt lgkmcnt(0)
	v_and_or_b32 v142, v142, s90, v240
	v_and_or_b32 v143, v143, s90, v240
	global_load_dwordx4 v[32:35], v142, s[80:81]
	global_load_dwordx4 v[36:39], v143, s[80:81]
	v_pk_fma_f32 v[112:113], v[78:79], v[106:107], v[112:113]
	v_pk_fma_f32 v[114:115], v[78:79], v[110:111], v[114:115]
	v_add_f32_e32 v96, v112, v113
	v_add_f32_e32 v97, v114, v115
	ds_bpermute_b32 v142, v251, v135
	ds_bpermute_b32 v143, v252, v135
	s_waitcnt vmcnt(16)
	v_cvt_pk_f32_fp8_e32 v[104:105], v40
	v_cvt_pk_f32_fp8_e32 v[108:109], v44
	v_cvt_pk_f32_fp8_sdwa v[106:107], v40 src0_sel:WORD_1
	v_cvt_pk_f32_fp8_sdwa v[110:111], v44 src0_sel:WORD_1
	v_pk_mul_f32 v[112:113], v[64:65], v[104:105]
	v_pk_mul_f32 v[114:115], v[64:65], v[108:109]
	v_pk_fma_f32 v[112:113], v[66:67], v[106:107], v[112:113]
	v_pk_fma_f32 v[114:115], v[66:67], v[110:111], v[114:115]
	v_cvt_pk_f32_fp8_e32 v[104:105], v41
	v_cvt_pk_f32_fp8_e32 v[108:109], v45
	v_cvt_pk_f32_fp8_sdwa v[106:107], v41 src0_sel:WORD_1
	v_cvt_pk_f32_fp8_sdwa v[110:111], v45 src0_sel:WORD_1
	v_pk_fma_f32 v[112:113], v[68:69], v[104:105], v[112:113]
	v_pk_fma_f32 v[114:115], v[68:69], v[108:109], v[114:115]
	v_pk_fma_f32 v[112:113], v[70:71], v[106:107], v[112:113]
	v_pk_fma_f32 v[114:115], v[70:71], v[110:111], v[114:115]
	v_cvt_pk_f32_fp8_e32 v[104:105], v42
	v_cvt_pk_f32_fp8_e32 v[108:109], v46
	v_cvt_pk_f32_fp8_sdwa v[106:107], v42 src0_sel:WORD_1
	v_cvt_pk_f32_fp8_sdwa v[110:111], v46 src0_sel:WORD_1
	v_pk_fma_f32 v[112:113], v[72:73], v[104:105], v[112:113]
	v_pk_fma_f32 v[114:115], v[72:73], v[108:109], v[114:115]
	v_pk_fma_f32 v[112:113], v[74:75], v[106:107], v[112:113]
	v_pk_fma_f32 v[114:115], v[74:75], v[110:111], v[114:115]
	v_cvt_pk_f32_fp8_e32 v[104:105], v43
	v_cvt_pk_f32_fp8_e32 v[108:109], v47
	v_cvt_pk_f32_fp8_sdwa v[106:107], v43 src0_sel:WORD_1
	v_cvt_pk_f32_fp8_sdwa v[110:111], v47 src0_sel:WORD_1
	v_pk_fma_f32 v[112:113], v[76:77], v[104:105], v[112:113]
	v_pk_fma_f32 v[114:115], v[76:77], v[108:109], v[114:115]
	s_waitcnt lgkmcnt(0)
	v_and_or_b32 v142, v142, s90, v240
	v_and_or_b32 v143, v143, s90, v240
	global_load_dwordx4 v[40:43], v142, s[80:81]
	global_load_dwordx4 v[44:47], v143, s[80:81]
	v_pk_fma_f32 v[112:113], v[78:79], v[106:107], v[112:113]
	v_pk_fma_f32 v[114:115], v[78:79], v[110:111], v[114:115]
	v_add_f32_e32 v98, v112, v113
	v_add_f32_e32 v99, v114, v115
	ds_bpermute_b32 v142, v253, v135
	ds_bpermute_b32 v143, v254, v135
	s_waitcnt vmcnt(16)
	v_cvt_pk_f32_fp8_e32 v[104:105], v48
	v_cvt_pk_f32_fp8_e32 v[108:109], v52
	v_cvt_pk_f32_fp8_sdwa v[106:107], v48 src0_sel:WORD_1
	v_cvt_pk_f32_fp8_sdwa v[110:111], v52 src0_sel:WORD_1
	v_pk_mul_f32 v[112:113], v[64:65], v[104:105]
	v_pk_mul_f32 v[114:115], v[64:65], v[108:109]
	v_pk_fma_f32 v[112:113], v[66:67], v[106:107], v[112:113]
	v_pk_fma_f32 v[114:115], v[66:67], v[110:111], v[114:115]
	v_cvt_pk_f32_fp8_e32 v[104:105], v49
	v_cvt_pk_f32_fp8_e32 v[108:109], v53
	v_cvt_pk_f32_fp8_sdwa v[106:107], v49 src0_sel:WORD_1
	v_cvt_pk_f32_fp8_sdwa v[110:111], v53 src0_sel:WORD_1
	v_pk_fma_f32 v[112:113], v[68:69], v[104:105], v[112:113]
	v_pk_fma_f32 v[114:115], v[68:69], v[108:109], v[114:115]
	v_pk_fma_f32 v[112:113], v[70:71], v[106:107], v[112:113]
	v_pk_fma_f32 v[114:115], v[70:71], v[110:111], v[114:115]
	v_cvt_pk_f32_fp8_e32 v[104:105], v50
	v_cvt_pk_f32_fp8_e32 v[108:109], v54
	v_cvt_pk_f32_fp8_sdwa v[106:107], v50 src0_sel:WORD_1
	v_cvt_pk_f32_fp8_sdwa v[110:111], v54 src0_sel:WORD_1
	v_pk_fma_f32 v[112:113], v[72:73], v[104:105], v[112:113]
	v_pk_fma_f32 v[114:115], v[72:73], v[108:109], v[114:115]
	v_pk_fma_f32 v[112:113], v[74:75], v[106:107], v[112:113]
	v_pk_fma_f32 v[114:115], v[74:75], v[110:111], v[114:115]
	v_cvt_pk_f32_fp8_e32 v[104:105], v51
	v_cvt_pk_f32_fp8_e32 v[108:109], v55
	v_cvt_pk_f32_fp8_sdwa v[106:107], v51 src0_sel:WORD_1
	v_cvt_pk_f32_fp8_sdwa v[110:111], v55 src0_sel:WORD_1
	v_pk_fma_f32 v[112:113], v[76:77], v[104:105], v[112:113]
	v_pk_fma_f32 v[114:115], v[76:77], v[108:109], v[114:115]
	s_waitcnt lgkmcnt(0)
	v_and_or_b32 v142, v142, s90, v240
	v_and_or_b32 v143, v143, s90, v240
	global_load_dwordx4 v[48:51], v142, s[80:81]
	global_load_dwordx4 v[52:55], v143, s[80:81]
	v_pk_fma_f32 v[112:113], v[78:79], v[106:107], v[112:113]
	v_pk_fma_f32 v[114:115], v[78:79], v[110:111], v[114:115]
	v_add_f32_e32 v100, v112, v113
	v_add_f32_e32 v101, v114, v115
	ds_bpermute_b32 v142, v255, v135
	ds_bpermute_b32 v143, v153, v135
	s_waitcnt vmcnt(16)
	v_cvt_pk_f32_fp8_e32 v[104:105], v56
	v_cvt_pk_f32_fp8_e32 v[108:109], v60
	v_cvt_pk_f32_fp8_sdwa v[106:107], v56 src0_sel:WORD_1
	v_cvt_pk_f32_fp8_sdwa v[110:111], v60 src0_sel:WORD_1
	v_pk_mul_f32 v[112:113], v[64:65], v[104:105]
	v_pk_mul_f32 v[114:115], v[64:65], v[108:109]
	v_pk_fma_f32 v[112:113], v[66:67], v[106:107], v[112:113]
	v_pk_fma_f32 v[114:115], v[66:67], v[110:111], v[114:115]
	v_cvt_pk_f32_fp8_e32 v[104:105], v57
	v_cvt_pk_f32_fp8_e32 v[108:109], v61
	v_cvt_pk_f32_fp8_sdwa v[106:107], v57 src0_sel:WORD_1
	v_cvt_pk_f32_fp8_sdwa v[110:111], v61 src0_sel:WORD_1
	v_pk_fma_f32 v[112:113], v[68:69], v[104:105], v[112:113]
	v_pk_fma_f32 v[114:115], v[68:69], v[108:109], v[114:115]
	v_pk_fma_f32 v[112:113], v[70:71], v[106:107], v[112:113]
	v_pk_fma_f32 v[114:115], v[70:71], v[110:111], v[114:115]
	v_cvt_pk_f32_fp8_e32 v[104:105], v58
	v_cvt_pk_f32_fp8_e32 v[108:109], v62
	v_cvt_pk_f32_fp8_sdwa v[106:107], v58 src0_sel:WORD_1
	v_cvt_pk_f32_fp8_sdwa v[110:111], v62 src0_sel:WORD_1
	v_pk_fma_f32 v[112:113], v[72:73], v[104:105], v[112:113]
	v_pk_fma_f32 v[114:115], v[72:73], v[108:109], v[114:115]
	v_pk_fma_f32 v[112:113], v[74:75], v[106:107], v[112:113]
	v_pk_fma_f32 v[114:115], v[74:75], v[110:111], v[114:115]
	v_cvt_pk_f32_fp8_e32 v[104:105], v59
	v_cvt_pk_f32_fp8_e32 v[108:109], v63
	v_cvt_pk_f32_fp8_sdwa v[106:107], v59 src0_sel:WORD_1
	v_cvt_pk_f32_fp8_sdwa v[110:111], v63 src0_sel:WORD_1
	v_pk_fma_f32 v[112:113], v[76:77], v[104:105], v[112:113]
	v_pk_fma_f32 v[114:115], v[76:77], v[108:109], v[114:115]
	s_waitcnt lgkmcnt(0)
	v_and_or_b32 v142, v142, s90, v240
	v_and_or_b32 v143, v143, s90, v240
	global_load_dwordx4 v[56:59], v142, s[80:81]
	global_load_dwordx4 v[60:63], v143, s[80:81]
	v_pk_fma_f32 v[112:113], v[78:79], v[106:107], v[112:113]
	v_pk_fma_f32 v[114:115], v[78:79], v[110:111], v[114:115]
	v_add_f32_e32 v102, v112, v113
	v_add_f32_e32 v103, v114, v115
	s_add_u32 s92, s100, 2
	s_min_u32 s92, s92, 127
	s_and_b32 s92, s92, 15
	s_lshl_b32 vcc_lo, s92, 9
	s_add_u32 vcc_lo, vcc_lo, s101
	v_add_u32_e32 v116, vcc_lo, v234
	ds_read_b32 v134, v116
	ds_read_b32 v135, v116 offset:256
	s_lshl_b32 vcc_lo, s98, 9
	s_add_u32 vcc_lo, vcc_lo, s101
	s_add_u32 vcc_lo, vcc_lo, 0x10000
	v_add_u32_e32 v117, vcc_lo, v234
	ds_read_b32 v136, v117
	ds_read_b32 v137, v117 offset:256
	s_mov_b32 s88, 0xf0f0f0f0
	s_mov_b32 s89, 0xf0f0f0f0
	v_cndmask_b32_e64 v144, v88, v92, s[88:89]
	v_cndmask_b32_e64 v92, v92, v88, s[88:89]
	v_cndmask_b32_e64 v145, v89, v93, s[88:89]
	v_cndmask_b32_e64 v93, v93, v89, s[88:89]
	v_cndmask_b32_e64 v146, v90, v94, s[88:89]
	v_cndmask_b32_e64 v94, v94, v90, s[88:89]
	v_cndmask_b32_e64 v147, v91, v95, s[88:89]
	v_cndmask_b32_e64 v95, v95, v91, s[88:89]
	v_add_f32_dpp v88, v92, v144 row_half_mirror row_mask:0xf bank_mask:0xf
	v_add_f32_dpp v89, v93, v145 row_half_mirror row_mask:0xf bank_mask:0xf
	v_add_f32_dpp v90, v94, v146 row_half_mirror row_mask:0xf bank_mask:0xf
	v_add_f32_dpp v91, v95, v147 row_half_mirror row_mask:0xf bank_mask:0xf
	v_cndmask_b32_e64 v144, v96, v100, s[88:89]
	v_cndmask_b32_e64 v100, v100, v96, s[88:89]
	v_cndmask_b32_e64 v145, v97, v101, s[88:89]
	v_cndmask_b32_e64 v101, v101, v97, s[88:89]
	v_cndmask_b32_e64 v146, v98, v102, s[88:89]
	v_cndmask_b32_e64 v102, v102, v98, s[88:89]
	v_cndmask_b32_e64 v147, v99, v103, s[88:89]
	v_cndmask_b32_e64 v103, v103, v99, s[88:89]
	v_add_f32_dpp v96, v100, v144 row_half_mirror row_mask:0xf bank_mask:0xf
	v_add_f32_dpp v97, v101, v145 row_half_mirror row_mask:0xf bank_mask:0xf
	v_add_f32_dpp v98, v102, v146 row_half_mirror row_mask:0xf bank_mask:0xf
	v_add_f32_dpp v99, v103, v147 row_half_mirror row_mask:0xf bank_mask:0xf
	s_mov_b32 s88, 0xcccccccc
	s_mov_b32 s89, 0xcccccccc
	v_cndmask_b32_e64 v144, v88, v90, s[88:89]
	v_cndmask_b32_e64 v90, v90, v88, s[88:89]
	v_cndmask_b32_e64 v145, v89, v91, s[88:89]
	v_cndmask_b32_e64 v91, v91, v89, s[88:89]
	v_cndmask_b32_e64 v146, v96, v98, s[88:89]
	v_cndmask_b32_e64 v98, v98, v96, s[88:89]
	v_cndmask_b32_e64 v147, v97, v99, s[88:89]
	v_cndmask_b32_e64 v99, v99, v97, s[88:89]
	v_add_f32_dpp v88, v90, v144 quad_perm:[2,3,0,1] row_mask:0xf bank_mask:0xf
	v_add_f32_dpp v89, v91, v145 quad_perm:[2,3,0,1] row_mask:0xf bank_mask:0xf
	v_add_f32_dpp v96, v98, v146 quad_perm:[2,3,0,1] row_mask:0xf bank_mask:0xf
	v_add_f32_dpp v97, v99, v147 quad_perm:[2,3,0,1] row_mask:0xf bank_mask:0xf
	s_mov_b32 s88, 0xaaaaaaaa
	s_mov_b32 s89, 0xaaaaaaaa
	v_cndmask_b32_e64 v144, v88, v89, s[88:89]
	v_cndmask_b32_e64 v89, v89, v88, s[88:89]
	v_cndmask_b32_e64 v145, v96, v97, s[88:89]
	v_cndmask_b32_e64 v97, v97, v96, s[88:89]
	s_nop 1
	v_add_f32_dpp v88, v89, v144 quad_perm:[1,0,3,2] row_mask:0xf bank_mask:0xf
	v_add_f32_dpp v96, v97, v145 quad_perm:[1,0,3,2] row_mask:0xf bank_mask:0xf
	s_nop 0
	ds_bpermute_b32 v144, v239, v88
	ds_bpermute_b32 v145, v239, v96
	s_waitcnt lgkmcnt(0)
	v_add_f32_e32 v136, v136, v144
	v_add_f32_e32 v137, v137, v145
	ds_write_b32 v117, v136
	ds_write_b32 v117, v137 offset:256
	s_add_u32 s100, s100, 1
	s_cmp_lt_u32 s100, 128
	s_cbranch_scc1 .Lpg0_uloop
	s_waitcnt vmcnt(0) lgkmcnt(0)
	s_mov_b32 s2, 0

; #define PG_ISSUE(BUF, TAB, e0_) do { const int isrc_ = ((e0_) < 64) ? myi0 : myi1; \
;       _Pragma("unroll") for (int e = 0; e < 8; ++e) { const int idx_ = __builtin_amdgcn_readlane(isrc_, ((e0_) + e) & 63); \
;         BUF[e] = *(const u32x4*)((TAB) + (size_t)idx_ * 1024 + lane * 16); } } while (0)
; DEV void peer_gather(const Params& P, int l, int m0, const int* idxs, const float* gs) {
;     ...
;     for (int e0 = 0; e0 < 128; e0 += 16) {
;       PG_ISSUE(b1, V, e0 + 8);
;       if (e0 == 64 && i + 1 < 16) sort_lists(lane, ni0, ni1, ng0, ng1);
;       PG_V16(b0, e0);
;       if (e0 + 16 < 128) PG_ISSUE(b0, V, e0 + 16);
;       PG_V16(b1, e0 + 8);
;     }
.Lpg0_vloop:
	s_and_b32 s98, s100, 15
	s_lshr_b32 s99, s100, 4
	s_add_u32 s92, s100, 1
	s_min_u32 s92, s92, 127
	s_lshr_b32 s93, s92, 4
	s_and_b32 s92, s92, 15
	v_readfirstlane_b32 s82, v132
	v_readfirstlane_b32 s83, v133
	s_nop 4
	s_add_u32 vcc_lo, s3, s98
	s_lshl_b32 vcc_lo, vcc_lo, 12
	s_lshl_b32 vcc_hi, s99, 9
	s_add_u32 vcc_lo, vcc_lo, vcc_hi
	v_add_u32_e32 v119, vcc_lo, v238
	global_load_dword v80, v119, s[82:83]
	global_load_dword v81, v119, s[82:83] offset:32
	s_lshl_b32 vcc_lo, s93, 7
	v_add_u32_e32 v240, vcc_lo, v235
	s_waitcnt lgkmcnt(0)
	ds_bpermute_b32 v138, v249, v136
	ds_bpermute_b32 v140, v250, v136
	ds_bpermute_b32 v142, v249, v134
	ds_bpermute_b32 v143, v250, v134
	ds_bpermute_b32 v144, v251, v136
	ds_bpermute_b32 v146, v252, v136
	s_waitcnt vmcnt(18) lgkmcnt(4)
	v_cvt_pk_f32_fp8_e32 v[104:105], v0
	v_cvt_pk_f32_fp8_e32 v[108:109], v4
	v_cvt_pk_f32_fp8_sdwa v[106:107], v0 src0_sel:WORD_1
	v_cvt_pk_f32_fp8_sdwa v[110:111], v4 src0_sel:WORD_1
	v_pk_mul_f32 v[64:65], v[104:105], v[138:139] op_sel_hi:[1,0]
	v_pk_mul_f32 v[66:67], v[106:107], v[138:139] op_sel_hi:[1,0]
	v_pk_fma_f32 v[64:65], v[108:109], v[140:141], v[64:65] op_sel_hi:[1,0,1]
	v_pk_fma_f32 v[66:67], v[110:111], v[140:141], v[66:67] op_sel_hi:[1,0,1]
	v_cvt_pk_f32_fp8_e32 v[104:105], v1
	v_cvt_pk_f32_fp8_e32 v[108:109], v5
	v_cvt_pk_f32_fp8_sdwa v[106:107], v1 src0_sel:WORD_1
	v_cvt_pk_f32_fp8_sdwa v[110:111], v5 src0_sel:WORD_1
	v_pk_mul_f32 v[68:69], v[104:105], v[138:139] op_sel_hi:[1,0]
	v_pk_mul_f32 v[70:71], v[106:107], v[138:139] op_sel_hi:[1,0]
	v_pk_fma_f32 v[68:69], v[108:109], v[140:141], v[68:69] op_sel_hi:[1,0,1]
	v_pk_fma_f32 v[70:71], v[110:111], v[140:141], v[70:71] op_sel_hi:[1,0,1]
	v_cvt_pk_f32_fp8_e32 v[104:105], v2
	v_cvt_pk_f32_fp8_e32 v[108:109], v6
	v_cvt_pk_f32_fp8_sdwa v[106:107], v2 src0_sel:WORD_1
	v_cvt_pk_f32_fp8_sdwa v[110:111], v6 src0_sel:WORD_1
	v_pk_mul_f32 v[72:73], v[104:105], v[138:139] op_sel_hi:[1,0]
	v_pk_mul_f32 v[74:75], v[106:107], v[138:139] op_sel_hi:[1,0]
	v_pk_fma_f32 v[72:73], v[108:109], v[140:141], v[72:73] op_sel_hi:[1,0,1]
	v_pk_fma_f32 v[74:75], v[110:111], v[140:141], v[74:75] op_sel_hi:[1,0,1]
	v_cvt_pk_f32_fp8_e32 v[104:105], v3
	v_cvt_pk_f32_fp8_e32 v[108:109], v7
	v_cvt_pk_f32_fp8_sdwa v[106:107], v3 src0_sel:WORD_1
	v_cvt_pk_f32_fp8_sdwa v[110:111], v7 src0_sel:WORD_1
	v_pk_mul_f32 v[76:77], v[104:105], v[138:139] op_sel_hi:[1,0]
	v_pk_mul_f32 v[78:79], v[106:107], v[138:139] op_sel_hi:[1,0]
	s_waitcnt lgkmcnt(0)
	v_and_or_b32 v142, v142, s90, v240
	v_and_or_b32 v143, v143, s90, v240
	global_load_dwordx4 v[0:3], v142, s[80:81]
	global_load_dwordx4 v[4:7], v143, s[80:81]
	v_pk_fma_f32 v[76:77], v[108:109], v[140:141], v[76:77] op_sel_hi:[1,0,1]
	v_pk_fma_f32 v[78:79], v[110:111], v[140:141], v[78:79] op_sel_hi:[1,0,1]
	ds_bpermute_b32 v142, v251, v134
	ds_bpermute_b32 v143, v252, v134
	ds_bpermute_b32 v138, v253, v136
	ds_bpermute_b32 v140, v254, v136
	s_waitcnt vmcnt(18) lgkmcnt(4)
	v_cvt_pk_f32_fp8_e32 v[104:105], v8
	v_cvt_pk_f32_fp8_e32 v[108:109], v12
	v_cvt_pk_f32_fp8_sdwa v[106:107], v8 src0_sel:WORD_1
	v_cvt_pk_f32_fp8_sdwa v[110:111], v12 src0_sel:WORD_1
	v_pk_fma_f32 v[64:65], v[104:105], v[144:145], v[64:65] op_sel_hi:[1,0,1]
	v_pk_fma_f32 v[66:67], v[106:107], v[144:145], v[66:67] op_sel_hi:[1,0,1]
	v_pk_fma_f32 v[64:65], v[108:109], v[146:147], v[64:65] op_sel_hi:[1,0,1]
	v_pk_fma_f32 v[66:67], v[110:111], v[146:147], v[66:67] op_sel_hi:[1,0,1]
	v_cvt_pk_f32_fp8_e32 v[104:105], v9
	v_cvt_pk_f32_fp8_e32 v[108:109], v13
	v_cvt_pk_f32_fp8_sdwa v[106:107], v9 src0_sel:WORD_1
	v_cvt_pk_f32_fp8_sdwa v[110:111], v13 src0_sel:WORD_1
	v_pk_fma_f32 v[68:69], v[104:105], v[144:145], v[68:69] op_sel_hi:[1,0,1]
	v_pk_fma_f32 v[70:71], v[106:107], v[144:145], v[70:71] op_sel_hi:[1,0,1]
	v_pk_fma_f32 v[68:69], v[108:109], v[146:147], v[68:69] op_sel_hi:[1,0,1]
	v_pk_fma_f32 v[70:71], v[110:111], v[146:147], v[70:71] op_sel_hi:[1,0,1]
	v_cvt_pk_f32_fp8_e32 v[104:105], v10
	v_cvt_pk_f32_fp8_e32 v[108:109], v14
	v_cvt_pk_f32_fp8_sdwa v[106:107], v10 src0_sel:WORD_1
	v_cvt_pk_f32_fp8_sdwa v[110:111], v14 src0_sel:WORD_1
	v_pk_fma_f32 v[72:73], v[104:105], v[144:145], v[72:73] op_sel_hi:[1,0,1]
	v_pk_fma_f32 v[74:75], v[106:107], v[144:145], v[74:75] op_sel_hi:[1,0,1]
	v_pk_fma_f32 v[72:73], v[108:109], v[146:147], v[72:73] op_sel_hi:[1,0,1]
	v_pk_fma_f32 v[74:75], v[110:111], v[146:147], v[74:75] op_sel_hi:[1,0,1]
	v_cvt_pk_f32_fp8_e32 v[104:105], v11
	v_cvt_pk_f32_fp8_e32 v[108:109], v15
	v_cvt_pk_f32_fp8_sdwa v[106:107], v11 src0_sel:WORD_1
	v_cvt_pk_f32_fp8_sdwa v[110:111], v15 src0_sel:WORD_1
	v_pk_fma_f32 v[76:77], v[104:105], v[144:145], v[76:77] op_sel_hi:[1,0,1]
	v_pk_fma_f32 v[78:79], v[106:107], v[144:145], v[78:79] op_sel_hi:[1,0,1]
	s_waitcnt lgkmcnt(0)
	v_and_or_b32 v142, v142, s90, v240
	v_and_or_b32 v143, v143, s90, v240
	global_load_dwordx4 v[8:11], v142, s[80:81]
	global_load_dwordx4 v[12:15], v143, s[80:81]
	v_pk_fma_f32 v[76:77], v[108:109], v[146:147], v[76:77] op_sel_hi:[1,0,1]
	v_pk_fma_f32 v[78:79], v[110:111], v[146:147], v[78:79] op_sel_hi:[1,0,1]
	ds_bpermute_b32 v142, v253, v134
	ds_bpermute_b32 v143, v254, v134
	ds_bpermute_b32 v144, v255, v136
	ds_bpermute_b32 v146, v153, v136
	s_waitcnt vmcnt(18) lgkmcnt(4)
	v_cvt_pk_f32_fp8_e32 v[104:105], v16
	v_cvt_pk_f32_fp8_e32 v[108:109], v20
	v_cvt_pk_f32_fp8_sdwa v[106:107], v16 src0_sel:WORD_1
	v_cvt_pk_f32_fp8_sdwa v[110:111], v20 src0_sel:WORD_1
	v_pk_fma_f32 v[64:65], v[104:105], v[138:139], v[64:65] op_sel_hi:[1,0,1]
	v_pk_fma_f32 v[66:67], v[106:107], v[138:139], v[66:67] op_sel_hi:[1,0,1]
	v_pk_fma_f32 v[64:65], v[108:109], v[140:141], v[64:65] op_sel_hi:[1,0,1]
	v_pk_fma_f32 v[66:67], v[110:111], v[140:141], v[66:67] op_sel_hi:[1,0,1]
	v_cvt_pk_f32_fp8_e32 v[104:105], v17
	v_cvt_pk_f32_fp8_e32 v[108:109], v21
	v_cvt_pk_f32_fp8_sdwa v[106:107], v17 src0_sel:WORD_1
	v_cvt_pk_f32_fp8_sdwa v[110:111], v21 src0_sel:WORD_1
	v_pk_fma_f32 v[68:69], v[104:105], v[138:139], v[68:69] op_sel_hi:[1,0,1]
	v_pk_fma_f32 v[70:71], v[106:107], v[138:139], v[70:71] op_sel_hi:[1,0,1]
	v_pk_fma_f32 v[68:69], v[108:109], v[140:141], v[68:69] op_sel_hi:[1,0,1]
	v_pk_fma_f32 v[70:71], v[110:111], v[140:141], v[70:71] op_sel_hi:[1,0,1]
	v_cvt_pk_f32_fp8_e32 v[104:105], v18
	v_cvt_pk_f32_fp8_e32 v[108:109], v22
	v_cvt_pk_f32_fp8_sdwa v[106:107], v18 src0_sel:WORD_1
	v_cvt_pk_f32_fp8_sdwa v[110:111], v22 src0_sel:WORD_1
	v_pk_fma_f32 v[72:73], v[104:105], v[138:139], v[72:73] op_sel_hi:[1,0,1]
	v_pk_fma_f32 v[74:75], v[106:107], v[138:139], v[74:75] op_sel_hi:[1,0,1]
	v_pk_fma_f32 v[72:73], v[108:109], v[140:141], v[72:73] op_sel_hi:[1,0,1]
	v_pk_fma_f32 v[74:75], v[110:111], v[140:141], v[74:75] op_sel_hi:[1,0,1]
	v_cvt_pk_f32_fp8_e32 v[104:105], v19
	v_cvt_pk_f32_fp8_e32 v[108:109], v23
	v_cvt_pk_f32_fp8_sdwa v[106:107], v19 src0_sel:WORD_1
	v_cvt_pk_f32_fp8_sdwa v[110:111], v23 src0_sel:WORD_1
	v_pk_fma_f32 v[76:77], v[104:105], v[138:139], v[76:77] op_sel_hi:[1,0,1]
	v_pk_fma_f32 v[78:79], v[106:107], v[138:139], v[78:79] op_sel_hi:[1,0,1]
	s_waitcnt lgkmcnt(0)
	v_and_or_b32 v142, v142, s90, v240
	v_and_or_b32 v143, v143, s90, v240
	global_load_dwordx4 v[16:19], v142, s[80:81]
	global_load_dwordx4 v[20:23], v143, s[80:81]
	v_pk_fma_f32 v[76:77], v[108:109], v[140:141], v[76:77] op_sel_hi:[1,0,1]
	v_pk_fma_f32 v[78:79], v[110:111], v[140:141], v[78:79] op_sel_hi:[1,0,1]
	ds_bpermute_b32 v142, v255, v134
	ds_bpermute_b32 v143, v153, v134
	ds_bpermute_b32 v138, v249, v137
	ds_bpermute_b32 v140, v250, v137
	s_waitcnt vmcnt(18) lgkmcnt(4)
	v_cvt_pk_f32_fp8_e32 v[104:105], v24
	v_cvt_pk_f32_fp8_e32 v[108:109], v28
	v_cvt_pk_f32_fp8_sdwa v[106:107], v24 src0_sel:WORD_1
	v_cvt_pk_f32_fp8_sdwa v[110:111], v28 src0_sel:WORD_1
	v_pk_fma_f32 v[64:65], v[104:105], v[144:145], v[64:65] op_sel_hi:[1,0,1]
	v_pk_fma_f32 v[66:67], v[106:107], v[144:145], v[66:67] op_sel_hi:[1,0,1]
	v_pk_fma_f32 v[64:65], v[108:109], v[146:147], v[64:65] op_sel_hi:[1,0,1]
	v_pk_fma_f32 v[66:67], v[110:111], v[146:147], v[66:67] op_sel_hi:[1,0,1]
	v_cvt_pk_f32_fp8_e32 v[104:105], v25
	v_cvt_pk_f32_fp8_e32 v[108:109], v29
	v_cvt_pk_f32_fp8_sdwa v[106:107], v25 src0_sel:WORD_1
	v_cvt_pk_f32_fp8_sdwa v[110:111], v29 src0_sel:WORD_1
	v_pk_fma_f32 v[68:69], v[104:105], v[144:145], v[68:69] op_sel_hi:[1,0,1]
	v_pk_fma_f32 v[70:71], v[106:107], v[144:145], v[70:71] op_sel_hi:[1,0,1]
	v_pk_fma_f32 v[68:69], v[108:109], v[146:147], v[68:69] op_sel_hi:[1,0,1]
	v_pk_fma_f32 v[70:71], v[110:111], v[146:147], v[70:71] op_sel_hi:[1,0,1]
	v_cvt_pk_f32_fp8_e32 v[104:105], v26
	v_cvt_pk_f32_fp8_e32 v[108:109], v30
	v_cvt_pk_f32_fp8_sdwa v[106:107], v26 src0_sel:WORD_1
	v_cvt_pk_f32_fp8_sdwa v[110:111], v30 src0_sel:WORD_1
	v_pk_fma_f32 v[72:73], v[104:105], v[144:145], v[72:73] op_sel_hi:[1,0,1]
	v_pk_fma_f32 v[74:75], v[106:107], v[144:145], v[74:75] op_sel_hi:[1,0,1]
	v_pk_fma_f32 v[72:73], v[108:109], v[146:147], v[72:73] op_sel_hi:[1,0,1]
	v_pk_fma_f32 v[74:75], v[110:111], v[146:147], v[74:75] op_sel_hi:[1,0,1]
	v_cvt_pk_f32_fp8_e32 v[104:105], v27
	v_cvt_pk_f32_fp8_e32 v[108:109], v31
	v_cvt_pk_f32_fp8_sdwa v[106:107], v27 src0_sel:WORD_1
	v_cvt_pk_f32_fp8_sdwa v[110:111], v31 src0_sel:WORD_1
	v_pk_fma_f32 v[76:77], v[104:105], v[144:145], v[76:77] op_sel_hi:[1,0,1]
	v_pk_fma_f32 v[78:79], v[106:107], v[144:145], v[78:79] op_sel_hi:[1,0,1]
	s_waitcnt lgkmcnt(0)
	v_and_or_b32 v142, v142, s90, v240
	v_and_or_b32 v143, v143, s90, v240
	global_load_dwordx4 v[24:27], v142, s[80:81]
	global_load_dwordx4 v[28:31], v143, s[80:81]
	v_pk_fma_f32 v[76:77], v[108:109], v[146:147], v[76:77] op_sel_hi:[1,0,1]
	v_pk_fma_f32 v[78:79], v[110:111], v[146:147], v[78:79] op_sel_hi:[1,0,1]
	ds_bpermute_b32 v142, v249, v135
	ds_bpermute_b32 v143, v250, v135
	ds_bpermute_b32 v144, v251, v137
	ds_bpermute_b32 v146, v252, v137
	s_waitcnt vmcnt(18) lgkmcnt(4)
	v_cvt_pk_f32_fp8_e32 v[104:105], v32
	v_cvt_pk_f32_fp8_e32 v[108:109], v36
	v_cvt_pk_f32_fp8_sdwa v[106:107], v32 src0_sel:WORD_1
	v_cvt_pk_f32_fp8_sdwa v[110:111], v36 src0_sel:WORD_1
	v_pk_fma_f32 v[64:65], v[104:105], v[138:139], v[64:65] op_sel_hi:[1,0,1]
	v_pk_fma_f32 v[66:67], v[106:107], v[138:139], v[66:67] op_sel_hi:[1,0,1]
	v_pk_fma_f32 v[64:65], v[108:109], v[140:141], v[64:65] op_sel_hi:[1,0,1]
	v_pk_fma_f32 v[66:67], v[110:111], v[140:141], v[66:67] op_sel_hi:[1,0,1]
	v_cvt_pk_f32_fp8_e32 v[104:105], v33
	v_cvt_pk_f32_fp8_e32 v[108:109], v37
	v_cvt_pk_f32_fp8_sdwa v[106:107], v33 src0_sel:WORD_1
	v_cvt_pk_f32_fp8_sdwa v[110:111], v37 src0_sel:WORD_1
	v_pk_fma_f32 v[68:69], v[104:105], v[138:139], v[68:69] op_sel_hi:[1,0,1]
	v_pk_fma_f32 v[70:71], v[106:107], v[138:139], v[70:71] op_sel_hi:[1,0,1]
	v_pk_fma_f32 v[68:69], v[108:109], v[140:141], v[68:69] op_sel_hi:[1,0,1]
	v_pk_fma_f32 v[70:71], v[110:111], v[140:141], v[70:71] op_sel_hi:[1,0,1]
	v_cvt_pk_f32_fp8_e32 v[104:105], v34
	v_cvt_pk_f32_fp8_e32 v[108:109], v38
	v_cvt_pk_f32_fp8_sdwa v[106:107], v34 src0_sel:WORD_1
	v_cvt_pk_f32_fp8_sdwa v[110:111], v38 src0_sel:WORD_1
	v_pk_fma_f32 v[72:73], v[104:105], v[138:139], v[72:73] op_sel_hi:[1,0,1]
	v_pk_fma_f32 v[74:75], v[106:107], v[138:139], v[74:75] op_sel_hi:[1,0,1]
	v_pk_fma_f32 v[72:73], v[108:109], v[140:141], v[72:73] op_sel_hi:[1,0,1]
	v_pk_fma_f32 v[74:75], v[110:111], v[140:141], v[74:75] op_sel_hi:[1,0,1]
	v_cvt_pk_f32_fp8_e32 v[104:105], v35
	v_cvt_pk_f32_fp8_e32 v[108:109], v39
	v_cvt_pk_f32_fp8_sdwa v[106:107], v35 src0_sel:WORD_1
	v_cvt_pk_f32_fp8_sdwa v[110:111], v39 src0_sel:WORD_1
	v_pk_fma_f32 v[76:77], v[104:105], v[138:139], v[76:77] op_sel_hi:[1,0,1]
	v_pk_fma_f32 v[78:79], v[106:107], v[138:139], v[78:79] op_sel_hi:[1,0,1]
	s_waitcnt lgkmcnt(0)
	v_and_or_b32 v142, v142, s90, v240
	v_and_or_b32 v143, v143, s90, v240
	global_load_dwordx4 v[32:35], v142, s[80:81]
	global_load_dwordx4 v[36:39], v143, s[80:81]
	v_pk_fma_f32 v[76:77], v[108:109], v[140:141], v[76:77] op_sel_hi:[1,0,1]
	v_pk_fma_f32 v[78:79], v[110:111], v[140:141], v[78:79] op_sel_hi:[1,0,1]
	ds_bpermute_b32 v142, v251, v135
	ds_bpermute_b32 v143, v252, v135
	ds_bpermute_b32 v138, v253, v137
	ds_bpermute_b32 v140, v254, v137
	s_waitcnt vmcnt(18) lgkmcnt(4)
	v_cvt_pk_f32_fp8_e32 v[104:105], v40
	v_cvt_pk_f32_fp8_e32 v[108:109], v44
	v_cvt_pk_f32_fp8_sdwa v[106:107], v40 src0_sel:WORD_1
	v_cvt_pk_f32_fp8_sdwa v[110:111], v44 src0_sel:WORD_1
	v_pk_fma_f32 v[64:65], v[104:105], v[144:145], v[64:65] op_sel_hi:[1,0,1]
	v_pk_fma_f32 v[66:67], v[106:107], v[144:145], v[66:67] op_sel_hi:[1,0,1]
	v_pk_fma_f32 v[64:65], v[108:109], v[146:147], v[64:65] op_sel_hi:[1,0,1]
	v_pk_fma_f32 v[66:67], v[110:111], v[146:147], v[66:67] op_sel_hi:[1,0,1]
	v_cvt_pk_f32_fp8_e32 v[104:105], v41
	v_cvt_pk_f32_fp8_e32 v[108:109], v45
	v_cvt_pk_f32_fp8_sdwa v[106:107], v41 src0_sel:WORD_1
	v_cvt_pk_f32_fp8_sdwa v[110:111], v45 src0_sel:WORD_1
	v_pk_fma_f32 v[68:69], v[104:105], v[144:145], v[68:69] op_sel_hi:[1,0,1]
	v_pk_fma_f32 v[70:71], v[106:107], v[144:145], v[70:71] op_sel_hi:[1,0,1]
	v_pk_fma_f32 v[68:69], v[108:109], v[146:147], v[68:69] op_sel_hi:[1,0,1]
	v_pk_fma_f32 v[70:71], v[110:111], v[146:147], v[70:71] op_sel_hi:[1,0,1]
	v_cvt_pk_f32_fp8_e32 v[104:105], v42
	v_cvt_pk_f32_fp8_e32 v[108:109], v46
	v_cvt_pk_f32_fp8_sdwa v[106:107], v42 src0_sel:WORD_1
	v_cvt_pk_f32_fp8_sdwa v[110:111], v46 src0_sel:WORD_1
	v_pk_fma_f32 v[72:73], v[104:105], v[144:145], v[72:73] op_sel_hi:[1,0,1]
	v_pk_fma_f32 v[74:75], v[106:107], v[144:145], v[74:75] op_sel_hi:[1,0,1]
	v_pk_fma_f32 v[72:73], v[108:109], v[146:147], v[72:73] op_sel_hi:[1,0,1]
	v_pk_fma_f32 v[74:75], v[110:111], v[146:147], v[74:75] op_sel_hi:[1,0,1]
	v_cvt_pk_f32_fp8_e32 v[104:105], v43
	v_cvt_pk_f32_fp8_e32 v[108:109], v47
	v_cvt_pk_f32_fp8_sdwa v[106:107], v43 src0_sel:WORD_1
	v_cvt_pk_f32_fp8_sdwa v[110:111], v47 src0_sel:WORD_1
	v_pk_fma_f32 v[76:77], v[104:105], v[144:145], v[76:77] op_sel_hi:[1,0,1]
	v_pk_fma_f32 v[78:79], v[106:107], v[144:145], v[78:79] op_sel_hi:[1,0,1]
	s_waitcnt lgkmcnt(0)
	v_and_or_b32 v142, v142, s90, v240
	v_and_or_b32 v143, v143, s90, v240
	global_load_dwordx4 v[40:43], v142, s[80:81]
	global_load_dwordx4 v[44:47], v143, s[80:81]
	v_pk_fma_f32 v[76:77], v[108:109], v[146:147], v[76:77] op_sel_hi:[1,0,1]
	v_pk_fma_f32 v[78:79], v[110:111], v[146:147], v[78:79] op_sel_hi:[1,0,1]
	ds_bpermute_b32 v142, v253, v135
	ds_bpermute_b32 v143, v254, v135
	ds_bpermute_b32 v144, v255, v137
	ds_bpermute_b32 v146, v153, v137
	s_waitcnt vmcnt(18) lgkmcnt(4)
	v_cvt_pk_f32_fp8_e32 v[104:105], v48
	v_cvt_pk_f32_fp8_e32 v[108:109], v52
	v_cvt_pk_f32_fp8_sdwa v[106:107], v48 src0_sel:WORD_1
	v_cvt_pk_f32_fp8_sdwa v[110:111], v52 src0_sel:WORD_1
	v_pk_fma_f32 v[64:65], v[104:105], v[138:139], v[64:65] op_sel_hi:[1,0,1]
	v_pk_fma_f32 v[66:67], v[106:107], v[138:139], v[66:67] op_sel_hi:[1,0,1]
	v_pk_fma_f32 v[64:65], v[108:109], v[140:141], v[64:65] op_sel_hi:[1,0,1]
	v_pk_fma_f32 v[66:67], v[110:111], v[140:141], v[66:67] op_sel_hi:[1,0,1]
	v_cvt_pk_f32_fp8_e32 v[104:105], v49
	v_cvt_pk_f32_fp8_e32 v[108:109], v53
	v_cvt_pk_f32_fp8_sdwa v[106:107], v49 src0_sel:WORD_1
	v_cvt_pk_f32_fp8_sdwa v[110:111], v53 src0_sel:WORD_1
	v_pk_fma_f32 v[68:69], v[104:105], v[138:139], v[68:69] op_sel_hi:[1,0,1]
	v_pk_fma_f32 v[70:71], v[106:107], v[138:139], v[70:71] op_sel_hi:[1,0,1]
	v_pk_fma_f32 v[68:69], v[108:109], v[140:141], v[68:69] op_sel_hi:[1,0,1]
	v_pk_fma_f32 v[70:71], v[110:111], v[140:141], v[70:71] op_sel_hi:[1,0,1]
	v_cvt_pk_f32_fp8_e32 v[104:105], v50
	v_cvt_pk_f32_fp8_e32 v[108:109], v54
	v_cvt_pk_f32_fp8_sdwa v[106:107], v50 src0_sel:WORD_1
	v_cvt_pk_f32_fp8_sdwa v[110:111], v54 src0_sel:WORD_1
	v_pk_fma_f32 v[72:73], v[104:105], v[138:139], v[72:73] op_sel_hi:[1,0,1]
	v_pk_fma_f32 v[74:75], v[106:107], v[138:139], v[74:75] op_sel_hi:[1,0,1]
	v_pk_fma_f32 v[72:73], v[108:109], v[140:141], v[72:73] op_sel_hi:[1,0,1]
	v_pk_fma_f32 v[74:75], v[110:111], v[140:141], v[74:75] op_sel_hi:[1,0,1]
	v_cvt_pk_f32_fp8_e32 v[104:105], v51
	v_cvt_pk_f32_fp8_e32 v[108:109], v55
	v_cvt_pk_f32_fp8_sdwa v[106:107], v51 src0_sel:WORD_1
	v_cvt_pk_f32_fp8_sdwa v[110:111], v55 src0_sel:WORD_1
	v_pk_fma_f32 v[76:77], v[104:105], v[138:139], v[76:77] op_sel_hi:[1,0,1]
	v_pk_fma_f32 v[78:79], v[106:107], v[138:139], v[78:79] op_sel_hi:[1,0,1]
	s_waitcnt lgkmcnt(0)
	v_and_or_b32 v142, v142, s90, v240
	v_and_or_b32 v143, v143, s90, v240
	global_load_dwordx4 v[48:51], v142, s[80:81]
	global_load_dwordx4 v[52:55], v143, s[80:81]
	v_pk_fma_f32 v[76:77], v[108:109], v[140:141], v[76:77] op_sel_hi:[1,0,1]
	v_pk_fma_f32 v[78:79], v[110:111], v[140:141], v[78:79] op_sel_hi:[1,0,1]
	ds_bpermute_b32 v142, v255, v135
	ds_bpermute_b32 v143, v153, v135
	s_waitcnt vmcnt(18) lgkmcnt(2)
; DEV void peer_gather(const Params& P, int l, int m0, const int* idxs, const float* gs) {
;     ...
;     float ss = 0.f;
; #pragma unroll
;     for (int q = 0; q < 4; ++q) {
;       hv[q][0] += acc[2 * q][0] * TAB_INV; hv[q][1] += acc[2 * q][1] * TAB_INV; hv[q][2] += acc[2 * q + 1][0] * TAB_INV; hv[q][3] += acc[2 * q + 1][1] * TAB_INV;
;       ss += hv[q][0] * hv[q][0] + hv[q][1] * hv[q][1] + hv[q][2] * hv[q][2] + hv[q][3] * hv[q][3];
;       *(f32x4*)(hrow + 4 * q) = hv[q];
;     }
;     const float rstd = rsqrtf(wave_sum(ss) * (1.f / DM) + EPS);
;     u32x4 oa, ob;
; #pragma unroll
;     for (int q = 0; q < 4; ++q) {
;       const f32x4 g = *(const f32x4*)(gp + lane * 16 + 4 * q);
	v_cvt_pk_f32_fp8_e32 v[104:105], v56
	v_cvt_pk_f32_fp8_e32 v[108:109], v60
	v_cvt_pk_f32_fp8_sdwa v[106:107], v56 src0_sel:WORD_1
	v_cvt_pk_f32_fp8_sdwa v[110:111], v60 src0_sel:WORD_1
	v_pk_fma_f32 v[64:65], v[104:105], v[144:145], v[64:65] op_sel_hi:[1,0,1]
	v_pk_fma_f32 v[66:67], v[106:107], v[144:145], v[66:67] op_sel_hi:[1,0,1]
	v_pk_fma_f32 v[64:65], v[108:109], v[146:147], v[64:65] op_sel_hi:[1,0,1]
	v_pk_fma_f32 v[66:67], v[110:111], v[146:147], v[66:67] op_sel_hi:[1,0,1]
	v_cvt_pk_f32_fp8_e32 v[104:105], v57
	v_cvt_pk_f32_fp8_e32 v[108:109], v61
	v_cvt_pk_f32_fp8_sdwa v[106:107], v57 src0_sel:WORD_1
	v_cvt_pk_f32_fp8_sdwa v[110:111], v61 src0_sel:WORD_1
	v_pk_fma_f32 v[68:69], v[104:105], v[144:145], v[68:69] op_sel_hi:[1,0,1]
	v_pk_fma_f32 v[70:71], v[106:107], v[144:145], v[70:71] op_sel_hi:[1,0,1]
	v_pk_fma_f32 v[68:69], v[108:109], v[146:147], v[68:69] op_sel_hi:[1,0,1]
	v_pk_fma_f32 v[70:71], v[110:111], v[146:147], v[70:71] op_sel_hi:[1,0,1]
	v_cvt_pk_f32_fp8_e32 v[104:105], v58
	v_cvt_pk_f32_fp8_e32 v[108:109], v62
	v_cvt_pk_f32_fp8_sdwa v[106:107], v58 src0_sel:WORD_1
	v_cvt_pk_f32_fp8_sdwa v[110:111], v62 src0_sel:WORD_1
	v_pk_fma_f32 v[72:73], v[104:105], v[144:145], v[72:73] op_sel_hi:[1,0,1]
	v_pk_fma_f32 v[74:75], v[106:107], v[144:145], v[74:75] op_sel_hi:[1,0,1]
	v_pk_fma_f32 v[72:73], v[108:109], v[146:147], v[72:73] op_sel_hi:[1,0,1]
	v_pk_fma_f32 v[74:75], v[110:111], v[146:147], v[74:75] op_sel_hi:[1,0,1]
	v_cvt_pk_f32_fp8_e32 v[104:105], v59
	v_cvt_pk_f32_fp8_e32 v[108:109], v63
	v_cvt_pk_f32_fp8_sdwa v[106:107], v59 src0_sel:WORD_1
	v_cvt_pk_f32_fp8_sdwa v[110:111], v63 src0_sel:WORD_1
	v_pk_fma_f32 v[76:77], v[104:105], v[144:145], v[76:77] op_sel_hi:[1,0,1]
	v_pk_fma_f32 v[78:79], v[106:107], v[144:145], v[78:79] op_sel_hi:[1,0,1]
	s_waitcnt lgkmcnt(0)
	v_and_or_b32 v142, v142, s90, v240
	v_and_or_b32 v143, v143, s90, v240
	global_load_dwordx4 v[56:59], v142, s[80:81]
	global_load_dwordx4 v[60:63], v143, s[80:81]
	v_pk_fma_f32 v[76:77], v[108:109], v[146:147], v[76:77] op_sel_hi:[1,0,1]
	v_pk_fma_f32 v[78:79], v[110:111], v[146:147], v[78:79] op_sel_hi:[1,0,1]
	s_add_u32 s92, s100, 2
	s_min_u32 s92, s92, 127
	s_and_b32 s92, s92, 15
	s_lshl_b32 vcc_lo, s92, 9
	s_add_u32 vcc_lo, vcc_lo, s101
	v_add_u32_e32 v116, vcc_lo, v234
	ds_read_b32 v134, v116
	ds_read_b32 v135, v116 offset:256
	s_add_u32 s92, s100, 1
	s_min_u32 s92, s92, 127
	s_and_b32 s92, s92, 15
	s_lshl_b32 vcc_lo, s92, 9
	s_add_u32 vcc_lo, vcc_lo, s101
	s_add_u32 vcc_lo, vcc_lo, 0x10000
	v_add_u32_e32 v117, vcc_lo, v234
	ds_read_b32 v136, v117
	ds_read_b32 v137, v117 offset:256
	s_nop 1
	v_permlane32_swap_b32_e32 v64, v65
	v_permlane32_swap_b32_e32 v66, v67
	v_permlane32_swap_b32_e32 v68, v69
	v_permlane32_swap_b32_e32 v70, v71
	v_permlane32_swap_b32_e32 v72, v73
	v_permlane32_swap_b32_e32 v74, v75
	v_permlane32_swap_b32_e32 v76, v77
	v_permlane32_swap_b32_e32 v78, v79
	v_add_f32_e32 v64, v64, v65
	v_add_f32_e32 v66, v66, v67
	v_add_f32_e32 v68, v68, v69
	v_add_f32_e32 v70, v70, v71
	v_add_f32_e32 v72, v72, v73
	v_add_f32_e32 v74, v74, v75
	v_add_f32_e32 v76, v76, v77
	v_add_f32_e32 v78, v78, v79
	s_nop 1
	v_permlane16_swap_b32_e32 v64, v66
	v_permlane16_swap_b32_e32 v68, v70
	v_permlane16_swap_b32_e32 v72, v74
	v_permlane16_swap_b32_e32 v76, v78
	v_add_f32_e32 v64, v64, v66
	v_add_f32_e32 v68, v68, v70
	v_add_f32_e32 v72, v72, v74
	v_add_f32_e32 v76, v76, v78
	s_mov_b32 s88, 0xff00ff00
	s_mov_b32 s89, 0xff00ff00
	s_nop 0
	v_cndmask_b32_e64 v65, v64, v68, s[88:89]
	v_cndmask_b32_e64 v66, v68, v64, s[88:89]
	v_cndmask_b32_e64 v73, v72, v76, s[88:89]
	v_cndmask_b32_e64 v74, v76, v72, s[88:89]
	s_nop 1
	v_add_f32_dpp v64, v66, v65 row_ror:8 row_mask:0xf bank_mask:0xf
	v_add_f32_dpp v72, v74, v73 row_ror:8 row_mask:0xf bank_mask:0xf
	s_waitcnt vmcnt(16)
	v_fmac_f32_e32 v80, 0x3c800000, v64
	v_fmac_f32_e32 v81, 0x3c800000, v72
	global_store_dword v119, v80, s[82:83]
	global_store_dword v119, v81, s[82:83] offset:32
	s_add_u32 s100, s100, 1
	s_cmp_lt_u32 s100, 128
	s_cbranch_scc1 .Lpg0_vloop
	s_waitcnt vmcnt(0) lgkmcnt(0)
	v_readfirstlane_b32 s88, v130
	v_readfirstlane_b32 s89, v131
	s_nop 4
	v_lshlrev_b32_e32 v117, 6, v233
	global_load_dwordx4 v[16:19], v117, s[88:89] offset:0
	global_load_dwordx4 v[20:23], v117, s[88:89] offset:16
	global_load_dwordx4 v[24:27], v117, s[88:89] offset:32
	global_load_dwordx4 v[28:31], v117, s[88:89] offset:48
	s_mov_b32 s2, 0
; DEV unsigned pk2(float lo, float hi) { f32x2_t v = {lo, hi}; bf16x2_t b = __builtin_convertvector(v, bf16x2_t); return __builtin_bit_cast(unsigned, b); }
; DEV void peer_gather(const Params& P, int l, int m0, const int* idxs, const float* gs) {
;     ...
;     const float rstd = rsqrtf(wave_sum(ss) * (1.f / DM) + EPS);
;     u32x4 oa, ob;
; #pragma unroll
;     for (int q = 0; q < 4; ++q) {
;       const f32x4 g = *(const f32x4*)(gp + lane * 16 + 4 * q);
;       const unsigned p0 = pk2(hv[q][0] * rstd * g[0], hv[q][1] * rstd * g[1]), p1 = pk2(hv[q][2] * rstd * g[2], hv[q][3] * rstd * g[3]);
;       if (q < 2) { oa[2 * q] = p0; oa[2 * q + 1] = p1; } else { ob[2 * (q - 2)] = p0; ob[2 * (q - 2) + 1] = p1; }
;     }
;     *(u32x4*)(hn + tok * DM + lane * 16) = oa; *(u32x4*)(hn + tok * DM + lane * 16 + 8) = ob;
.Lpg0_epi:
	v_readfirstlane_b32 s82, v132
	v_readfirstlane_b32 s83, v133
	s_nop 4
	v_readfirstlane_b32 s84, v128
	v_readfirstlane_b32 s85, v129
	s_nop 4
	s_add_u32 s98, s3, s2
	s_lshl_b32 vcc_lo, s98, 12
	v_lshl_add_u32 v116, v233, 6, vcc_lo
	global_load_dwordx4 v[0:3], v116, s[82:83] offset:0
	global_load_dwordx4 v[4:7], v116, s[82:83] offset:16
	global_load_dwordx4 v[8:11], v116, s[82:83] offset:32
	global_load_dwordx4 v[12:15], v116, s[82:83] offset:48
	s_add_u32 s99, s3, s2
	s_add_u32 s99, s99, 1
	s_lshl_b32 vcc_lo, s99, 12
	v_lshl_add_u32 v149, v233, 6, vcc_lo
	global_load_dwordx4 v[32:35], v149, s[82:83] offset:0
	global_load_dwordx4 v[36:39], v149, s[82:83] offset:16
	global_load_dwordx4 v[40:43], v149, s[82:83] offset:32
	global_load_dwordx4 v[44:47], v149, s[82:83] offset:48
	s_waitcnt vmcnt(4)
	v_pk_mul_f32 v[104:105], v[0:1], v[0:1]
	v_pk_fma_f32 v[104:105], v[2:3], v[2:3], v[104:105]
	v_pk_fma_f32 v[104:105], v[4:5], v[4:5], v[104:105]
	v_pk_fma_f32 v[104:105], v[6:7], v[6:7], v[104:105]
	v_pk_fma_f32 v[104:105], v[8:9], v[8:9], v[104:105]
	v_pk_fma_f32 v[104:105], v[10:11], v[10:11], v[104:105]
	v_pk_fma_f32 v[104:105], v[12:13], v[12:13], v[104:105]
	v_pk_fma_f32 v[104:105], v[14:15], v[14:15], v[104:105]
	v_add_f32_e32 v118, v104, v105
	s_nop 1
	v_add_f32_dpp v118, v118, v118 quad_perm:[1,0,3,2] row_mask:0xf bank_mask:0xf
	s_nop 1
	v_add_f32_dpp v118, v118, v118 quad_perm:[2,3,0,1] row_mask:0xf bank_mask:0xf
	s_nop 1
	v_add_f32_dpp v118, v118, v118 row_half_mirror row_mask:0xf bank_mask:0xf
	s_nop 1
	v_add_f32_dpp v118, v118, v118 row_mirror row_mask:0xf bank_mask:0xf
	v_xor_b32_e32 v119, 64, v234
	ds_bpermute_b32 v119, v119, v118
	s_waitcnt lgkmcnt(0)
	v_add_f32_e32 v118, v118, v119
	v_xor_b32_e32 v119, 128, v234
	ds_bpermute_b32 v119, v119, v118
	s_waitcnt lgkmcnt(0)
	v_add_f32_e32 v118, v118, v119
	v_mov_b32_e32 v119, 0x358637bd
	v_fmac_f32_e32 v119, 0x3a800000, v118
	v_rsq_f32_e32 v106, v119
	s_nop 1
	v_pk_mul_f32 v[0:1], v[0:1], v[106:107] op_sel_hi:[1,0]
	v_pk_mul_f32 v[2:3], v[2:3], v[106:107] op_sel_hi:[1,0]
	v_pk_mul_f32 v[4:5], v[4:5], v[106:107] op_sel_hi:[1,0]
	v_pk_mul_f32 v[6:7], v[6:7], v[106:107] op_sel_hi:[1,0]
	v_pk_mul_f32 v[8:9], v[8:9], v[106:107] op_sel_hi:[1,0]
	v_pk_mul_f32 v[10:11], v[10:11], v[106:107] op_sel_hi:[1,0]
	v_pk_mul_f32 v[12:13], v[12:13], v[106:107] op_sel_hi:[1,0]
	v_pk_mul_f32 v[14:15], v[14:15], v[106:107] op_sel_hi:[1,0]
	v_pk_mul_f32 v[0:1], v[16:17], v[0:1]
	v_pk_mul_f32 v[2:3], v[18:19], v[2:3]
	v_pk_mul_f32 v[4:5], v[20:21], v[4:5]
	v_pk_mul_f32 v[6:7], v[22:23], v[6:7]
	v_pk_mul_f32 v[8:9], v[24:25], v[8:9]
	v_pk_mul_f32 v[10:11], v[26:27], v[10:11]
	v_pk_mul_f32 v[12:13], v[28:29], v[12:13]
	v_pk_mul_f32 v[14:15], v[30:31], v[14:15]
	v_cvt_pk_bf16_f32 v48, v0, v1
	v_cvt_pk_bf16_f32 v49, v2, v3
	v_cvt_pk_bf16_f32 v50, v4, v5
	v_cvt_pk_bf16_f32 v51, v6, v7
	v_cvt_pk_bf16_f32 v52, v8, v9
	v_cvt_pk_bf16_f32 v53, v10, v11
	v_cvt_pk_bf16_f32 v54, v12, v13
	v_cvt_pk_bf16_f32 v55, v14, v15
	s_lshl_b32 vcc_lo, s98, 11
	v_lshl_add_u32 v116, v233, 5, vcc_lo
	global_store_dwordx4 v116, v[48:51], s[84:85]
	global_store_dwordx4 v116, v[52:55], s[84:85] offset:16
	s_waitcnt vmcnt(2)
	v_pk_mul_f32 v[104:105], v[32:33], v[32:33]
	v_pk_fma_f32 v[104:105], v[34:35], v[34:35], v[104:105]
	v_pk_fma_f32 v[104:105], v[36:37], v[36:37], v[104:105]
	v_pk_fma_f32 v[104:105], v[38:39], v[38:39], v[104:105]
	v_pk_fma_f32 v[104:105], v[40:41], v[40:41], v[104:105]
	v_pk_fma_f32 v[104:105], v[42:43], v[42:43], v[104:105]
	v_pk_fma_f32 v[104:105], v[44:45], v[44:45], v[104:105]
	v_pk_fma_f32 v[104:105], v[46:47], v[46:47], v[104:105]
	v_add_f32_e32 v118, v104, v105
	s_nop 1
	v_add_f32_dpp v118, v118, v118 quad_perm:[1,0,3,2] row_mask:0xf bank_mask:0xf
	s_nop 1
	v_add_f32_dpp v118, v118, v118 quad_perm:[2,3,0,1] row_mask:0xf bank_mask:0xf
	s_nop 1
	v_add_f32_dpp v118, v118, v118 row_half_mirror row_mask:0xf bank_mask:0xf
	s_nop 1
	v_add_f32_dpp v118, v118, v118 row_mirror row_mask:0xf bank_mask:0xf
	v_xor_b32_e32 v119, 64, v234
	ds_bpermute_b32 v119, v119, v118
	s_waitcnt lgkmcnt(0)
	v_add_f32_e32 v118, v118, v119
	v_xor_b32_e32 v119, 128, v234
	ds_bpermute_b32 v119, v119, v118
	s_waitcnt lgkmcnt(0)
	v_add_f32_e32 v118, v118, v119
	v_mov_b32_e32 v119, 0x358637bd
	v_fmac_f32_e32 v119, 0x3a800000, v118
	v_rsq_f32_e32 v106, v119
	s_nop 1
	v_pk_mul_f32 v[32:33], v[32:33], v[106:107] op_sel_hi:[1,0]
	v_pk_mul_f32 v[34:35], v[34:35], v[106:107] op_sel_hi:[1,0]
	v_pk_mul_f32 v[36:37], v[36:37], v[106:107] op_sel_hi:[1,0]
	v_pk_mul_f32 v[38:39], v[38:39], v[106:107] op_sel_hi:[1,0]
	v_pk_mul_f32 v[40:41], v[40:41], v[106:107] op_sel_hi:[1,0]
	v_pk_mul_f32 v[42:43], v[42:43], v[106:107] op_sel_hi:[1,0]
	v_pk_mul_f32 v[44:45], v[44:45], v[106:107] op_sel_hi:[1,0]
	v_pk_mul_f32 v[46:47], v[46:47], v[106:107] op_sel_hi:[1,0]
	v_pk_mul_f32 v[32:33], v[16:17], v[32:33]
	v_pk_mul_f32 v[34:35], v[18:19], v[34:35]
	v_pk_mul_f32 v[36:37], v[20:21], v[36:37]
	v_pk_mul_f32 v[38:39], v[22:23], v[38:39]
	v_pk_mul_f32 v[40:41], v[24:25], v[40:41]
	v_pk_mul_f32 v[42:43], v[26:27], v[42:43]
	v_pk_mul_f32 v[44:45], v[28:29], v[44:45]
	v_pk_mul_f32 v[46:47], v[30:31], v[46:47]
	v_cvt_pk_bf16_f32 v48, v32, v33
	v_cvt_pk_bf16_f32 v49, v34, v35
	v_cvt_pk_bf16_f32 v50, v36, v37
	v_cvt_pk_bf16_f32 v51, v38, v39
	v_cvt_pk_bf16_f32 v52, v40, v41
	v_cvt_pk_bf16_f32 v53, v42, v43
	v_cvt_pk_bf16_f32 v54, v44, v45
	v_cvt_pk_bf16_f32 v55, v46, v47
	s_lshl_b32 vcc_lo, s99, 11
	v_lshl_add_u32 v149, v233, 5, vcc_lo
	global_store_dwordx4 v149, v[48:51], s[84:85]
	global_store_dwordx4 v149, v[52:55], s[84:85] offset:16
	s_add_u32 s2, s2, 2
	s_cmp_lt_u32 s2, 16
	s_cbranch_scc1 .Lpg0_epi
	s_waitcnt vmcnt(0) lgkmcnt(0)
	v_readlane_b32 s90, v231, 30
	v_readlane_b32 s91, v231, 31

; #define PG_ISSUE(BUF, TAB, e0_) do { const int isrc_ = ((e0_) < 64) ? myi0 : myi1; \
;       _Pragma("unroll") for (int e = 0; e < 8; ++e) { const int idx_ = __builtin_amdgcn_readlane(isrc_, ((e0_) + e) & 63); \
;         BUF[e] = *(const u32x4*)((TAB) + (size_t)idx_ * 1024 + lane * 16); } } while (0)
; DEV void peer_gather(const Params& P, int l, int m0, const int* idxs, const float* gs) {
;     ...
;     PG_ISSUE(b0, U, 0);
; #pragma nounroll
;     for (int e0 = 0; e0 < 128; e0 += 16) {
;       PG_ISSUE(b1, U, e0 + 8);
;       PG_U8(b0, 0, e0);
;       if (e0 + 16 < 128) PG_ISSUE(b0, U, e0 + 16); else PG_ISSUE(b0, V, 0);
;       PG_U8(b1, 0, e0 + 8);
;     }
.Lpg1_uloop:
	s_and_b32 s98, s100, 15
	s_lshr_b32 s99, s100, 4
	s_add_u32 s92, s100, 1
	s_min_u32 s92, s92, 127
	s_lshr_b32 s93, s92, 4
	s_and_b32 s92, s92, 15
	s_waitcnt vmcnt(16)
	v_lshlrev_b32_e32 v64, 16, v80
	v_and_b32_e32 v65, 0xffff0000, v80
	v_lshlrev_b32_e32 v66, 16, v81
	v_and_b32_e32 v67, 0xffff0000, v81
	v_lshlrev_b32_e32 v68, 16, v82
	v_and_b32_e32 v69, 0xffff0000, v82
	v_lshlrev_b32_e32 v70, 16, v83
	v_and_b32_e32 v71, 0xffff0000, v83
	v_lshlrev_b32_e32 v72, 16, v84
	v_and_b32_e32 v73, 0xffff0000, v84
	v_lshlrev_b32_e32 v74, 16, v85
	v_and_b32_e32 v75, 0xffff0000, v85
	v_lshlrev_b32_e32 v76, 16, v86
	v_and_b32_e32 v77, 0xffff0000, v86
	v_lshlrev_b32_e32 v78, 16, v87
	v_and_b32_e32 v79, 0xffff0000, v87
	v_readfirstlane_b32 s82, v122
	v_readfirstlane_b32 s83, v123
	s_nop 4
	s_add_u32 vcc_lo, s3, s92
	s_lshl_b32 vcc_lo, vcc_lo, 11
	s_lshl_b32 vcc_hi, s93, 8
	s_add_u32 vcc_lo, vcc_lo, vcc_hi
	v_add_u32_e32 v119, vcc_lo, v236
	global_load_dwordx4 v[80:83], v119, s[82:83]
	global_load_dwordx4 v[84:87], v119, s[82:83] offset:16
	s_lshl_b32 vcc_lo, s93, 7
	v_add_u32_e32 v240, vcc_lo, v235
	s_waitcnt lgkmcnt(0)
	ds_bpermute_b32 v142, v249, v134
	ds_bpermute_b32 v143, v250, v134
	s_waitcnt vmcnt(16)
	v_cvt_pk_f32_fp8_e32 v[104:105], v0
	v_cvt_pk_f32_fp8_e32 v[108:109], v4
	v_cvt_pk_f32_fp8_sdwa v[106:107], v0 src0_sel:WORD_1
	v_cvt_pk_f32_fp8_sdwa v[110:111], v4 src0_sel:WORD_1
	v_pk_mul_f32 v[112:113], v[64:65], v[104:105]
	v_pk_mul_f32 v[114:115], v[64:65], v[108:109]
	v_pk_fma_f32 v[112:113], v[66:67], v[106:107], v[112:113]
	v_pk_fma_f32 v[114:115], v[66:67], v[110:111], v[114:115]
	v_cvt_pk_f32_fp8_e32 v[104:105], v1
	v_cvt_pk_f32_fp8_e32 v[108:109], v5
	v_cvt_pk_f32_fp8_sdwa v[106:107], v1 src0_sel:WORD_1
	v_cvt_pk_f32_fp8_sdwa v[110:111], v5 src0_sel:WORD_1
	v_pk_fma_f32 v[112:113], v[68:69], v[104:105], v[112:113]
	v_pk_fma_f32 v[114:115], v[68:69], v[108:109], v[114:115]
	v_pk_fma_f32 v[112:113], v[70:71], v[106:107], v[112:113]
	v_pk_fma_f32 v[114:115], v[70:71], v[110:111], v[114:115]
	v_cvt_pk_f32_fp8_e32 v[104:105], v2
	v_cvt_pk_f32_fp8_e32 v[108:109], v6
	v_cvt_pk_f32_fp8_sdwa v[106:107], v2 src0_sel:WORD_1
	v_cvt_pk_f32_fp8_sdwa v[110:111], v6 src0_sel:WORD_1
	v_pk_fma_f32 v[112:113], v[72:73], v[104:105], v[112:113]
	v_pk_fma_f32 v[114:115], v[72:73], v[108:109], v[114:115]
	v_pk_fma_f32 v[112:113], v[74:75], v[106:107], v[112:113]
	v_pk_fma_f32 v[114:115], v[74:75], v[110:111], v[114:115]
	v_cvt_pk_f32_fp8_e32 v[104:105], v3
	v_cvt_pk_f32_fp8_e32 v[108:109], v7
	v_cvt_pk_f32_fp8_sdwa v[106:107], v3 src0_sel:WORD_1
	v_cvt_pk_f32_fp8_sdwa v[110:111], v7 src0_sel:WORD_1
	v_pk_fma_f32 v[112:113], v[76:77], v[104:105], v[112:113]
	v_pk_fma_f32 v[114:115], v[76:77], v[108:109], v[114:115]
	s_waitcnt lgkmcnt(0)
	v_and_or_b32 v142, v142, s90, v240
	v_and_or_b32 v143, v143, s90, v240
	global_load_dwordx4 v[0:3], v142, s[80:81]
	global_load_dwordx4 v[4:7], v143, s[80:81]
	v_pk_fma_f32 v[112:113], v[78:79], v[106:107], v[112:113]
	v_pk_fma_f32 v[114:115], v[78:79], v[110:111], v[114:115]
	v_add_f32_e32 v88, v112, v113
	v_add_f32_e32 v89, v114, v115
	ds_bpermute_b32 v142, v251, v134
	ds_bpermute_b32 v143, v252, v134
	s_waitcnt vmcnt(16)
	v_cvt_pk_f32_fp8_e32 v[104:105], v8
	v_cvt_pk_f32_fp8_e32 v[108:109], v12
	v_cvt_pk_f32_fp8_sdwa v[106:107], v8 src0_sel:WORD_1
	v_cvt_pk_f32_fp8_sdwa v[110:111], v12 src0_sel:WORD_1
	v_pk_mul_f32 v[112:113], v[64:65], v[104:105]
	v_pk_mul_f32 v[114:115], v[64:65], v[108:109]
	v_pk_fma_f32 v[112:113], v[66:67], v[106:107], v[112:113]
	v_pk_fma_f32 v[114:115], v[66:67], v[110:111], v[114:115]
	v_cvt_pk_f32_fp8_e32 v[104:105], v9
	v_cvt_pk_f32_fp8_e32 v[108:109], v13
	v_cvt_pk_f32_fp8_sdwa v[106:107], v9 src0_sel:WORD_1
	v_cvt_pk_f32_fp8_sdwa v[110:111], v13 src0_sel:WORD_1
	v_pk_fma_f32 v[112:113], v[68:69], v[104:105], v[112:113]
	v_pk_fma_f32 v[114:115], v[68:69], v[108:109], v[114:115]
	v_pk_fma_f32 v[112:113], v[70:71], v[106:107], v[112:113]
	v_pk_fma_f32 v[114:115], v[70:71], v[110:111], v[114:115]
	v_cvt_pk_f32_fp8_e32 v[104:105], v10
	v_cvt_pk_f32_fp8_e32 v[108:109], v14
	v_cvt_pk_f32_fp8_sdwa v[106:107], v10 src0_sel:WORD_1
	v_cvt_pk_f32_fp8_sdwa v[110:111], v14 src0_sel:WORD_1
	v_pk_fma_f32 v[112:113], v[72:73], v[104:105], v[112:113]
	v_pk_fma_f32 v[114:115], v[72:73], v[108:109], v[114:115]
	v_pk_fma_f32 v[112:113], v[74:75], v[106:107], v[112:113]
	v_pk_fma_f32 v[114:115], v[74:75], v[110:111], v[114:115]
	v_cvt_pk_f32_fp8_e32 v[104:105], v11
	v_cvt_pk_f32_fp8_e32 v[108:109], v15
	v_cvt_pk_f32_fp8_sdwa v[106:107], v11 src0_sel:WORD_1
	v_cvt_pk_f32_fp8_sdwa v[110:111], v15 src0_sel:WORD_1
	v_pk_fma_f32 v[112:113], v[76:77], v[104:105], v[112:113]
	v_pk_fma_f32 v[114:115], v[76:77], v[108:109], v[114:115]
	s_waitcnt lgkmcnt(0)
	v_and_or_b32 v142, v142, s90, v240
	v_and_or_b32 v143, v143, s90, v240
	global_load_dwordx4 v[8:11], v142, s[80:81]
	global_load_dwordx4 v[12:15], v143, s[80:81]
	v_pk_fma_f32 v[112:113], v[78:79], v[106:107], v[112:113]
	v_pk_fma_f32 v[114:115], v[78:79], v[110:111], v[114:115]
	v_add_f32_e32 v90, v112, v113
	v_add_f32_e32 v91, v114, v115
	ds_bpermute_b32 v142, v253, v134
	ds_bpermute_b32 v143, v254, v134
	s_waitcnt vmcnt(16)
	v_cvt_pk_f32_fp8_e32 v[104:105], v16
	v_cvt_pk_f32_fp8_e32 v[108:109], v20
	v_cvt_pk_f32_fp8_sdwa v[106:107], v16 src0_sel:WORD_1
	v_cvt_pk_f32_fp8_sdwa v[110:111], v20 src0_sel:WORD_1
	v_pk_mul_f32 v[112:113], v[64:65], v[104:105]
	v_pk_mul_f32 v[114:115], v[64:65], v[108:109]
	v_pk_fma_f32 v[112:113], v[66:67], v[106:107], v[112:113]
	v_pk_fma_f32 v[114:115], v[66:67], v[110:111], v[114:115]
	v_cvt_pk_f32_fp8_e32 v[104:105], v17
	v_cvt_pk_f32_fp8_e32 v[108:109], v21
	v_cvt_pk_f32_fp8_sdwa v[106:107], v17 src0_sel:WORD_1
	v_cvt_pk_f32_fp8_sdwa v[110:111], v21 src0_sel:WORD_1
	v_pk_fma_f32 v[112:113], v[68:69], v[104:105], v[112:113]
	v_pk_fma_f32 v[114:115], v[68:69], v[108:109], v[114:115]
	v_pk_fma_f32 v[112:113], v[70:71], v[106:107], v[112:113]
	v_pk_fma_f32 v[114:115], v[70:71], v[110:111], v[114:115]
	v_cvt_pk_f32_fp8_e32 v[104:105], v18
	v_cvt_pk_f32_fp8_e32 v[108:109], v22
	v_cvt_pk_f32_fp8_sdwa v[106:107], v18 src0_sel:WORD_1
	v_cvt_pk_f32_fp8_sdwa v[110:111], v22 src0_sel:WORD_1
	v_pk_fma_f32 v[112:113], v[72:73], v[104:105], v[112:113]
	v_pk_fma_f32 v[114:115], v[72:73], v[108:109], v[114:115]
	v_pk_fma_f32 v[112:113], v[74:75], v[106:107], v[112:113]
	v_pk_fma_f32 v[114:115], v[74:75], v[110:111], v[114:115]
	v_cvt_pk_f32_fp8_e32 v[104:105], v19
	v_cvt_pk_f32_fp8_e32 v[108:109], v23
	v_cvt_pk_f32_fp8_sdwa v[106:107], v19 src0_sel:WORD_1
	v_cvt_pk_f32_fp8_sdwa v[110:111], v23 src0_sel:WORD_1
	v_pk_fma_f32 v[112:113], v[76:77], v[104:105], v[112:113]
	v_pk_fma_f32 v[114:115], v[76:77], v[108:109], v[114:115]
	s_waitcnt lgkmcnt(0)
	v_and_or_b32 v142, v142, s90, v240
	v_and_or_b32 v143, v143, s90, v240
	global_load_dwordx4 v[16:19], v142, s[80:81]
	global_load_dwordx4 v[20:23], v143, s[80:81]
	v_pk_fma_f32 v[112:113], v[78:79], v[106:107], v[112:113]
	v_pk_fma_f32 v[114:115], v[78:79], v[110:111], v[114:115]
	v_add_f32_e32 v92, v112, v113
	v_add_f32_e32 v93, v114, v115
	ds_bpermute_b32 v142, v255, v134
	ds_bpermute_b32 v143, v153, v134
	s_waitcnt vmcnt(16)
	v_cvt_pk_f32_fp8_e32 v[104:105], v24
	v_cvt_pk_f32_fp8_e32 v[108:109], v28
	v_cvt_pk_f32_fp8_sdwa v[106:107], v24 src0_sel:WORD_1
	v_cvt_pk_f32_fp8_sdwa v[110:111], v28 src0_sel:WORD_1
	v_pk_mul_f32 v[112:113], v[64:65], v[104:105]
	v_pk_mul_f32 v[114:115], v[64:65], v[108:109]
	v_pk_fma_f32 v[112:113], v[66:67], v[106:107], v[112:113]
	v_pk_fma_f32 v[114:115], v[66:67], v[110:111], v[114:115]
	v_cvt_pk_f32_fp8_e32 v[104:105], v25
	v_cvt_pk_f32_fp8_e32 v[108:109], v29
	v_cvt_pk_f32_fp8_sdwa v[106:107], v25 src0_sel:WORD_1
	v_cvt_pk_f32_fp8_sdwa v[110:111], v29 src0_sel:WORD_1
	v_pk_fma_f32 v[112:113], v[68:69], v[104:105], v[112:113]
	v_pk_fma_f32 v[114:115], v[68:69], v[108:109], v[114:115]
	v_pk_fma_f32 v[112:113], v[70:71], v[106:107], v[112:113]
	v_pk_fma_f32 v[114:115], v[70:71], v[110:111], v[114:115]
	v_cvt_pk_f32_fp8_e32 v[104:105], v26
	v_cvt_pk_f32_fp8_e32 v[108:109], v30
	v_cvt_pk_f32_fp8_sdwa v[106:107], v26 src0_sel:WORD_1
	v_cvt_pk_f32_fp8_sdwa v[110:111], v30 src0_sel:WORD_1
	v_pk_fma_f32 v[112:113], v[72:73], v[104:105], v[112:113]
	v_pk_fma_f32 v[114:115], v[72:73], v[108:109], v[114:115]
	v_pk_fma_f32 v[112:113], v[74:75], v[106:107], v[112:113]
	v_pk_fma_f32 v[114:115], v[74:75], v[110:111], v[114:115]
	v_cvt_pk_f32_fp8_e32 v[104:105], v27
	v_cvt_pk_f32_fp8_e32 v[108:109], v31
	v_cvt_pk_f32_fp8_sdwa v[106:107], v27 src0_sel:WORD_1
	v_cvt_pk_f32_fp8_sdwa v[110:111], v31 src0_sel:WORD_1
	v_pk_fma_f32 v[112:113], v[76:77], v[104:105], v[112:113]
	v_pk_fma_f32 v[114:115], v[76:77], v[108:109], v[114:115]
	s_waitcnt lgkmcnt(0)
	v_and_or_b32 v142, v142, s90, v240
	v_and_or_b32 v143, v143, s90, v240
	global_load_dwordx4 v[24:27], v142, s[80:81]
	global_load_dwordx4 v[28:31], v143, s[80:81]
	v_pk_fma_f32 v[112:113], v[78:79], v[106:107], v[112:113]
	v_pk_fma_f32 v[114:115], v[78:79], v[110:111], v[114:115]
	v_add_f32_e32 v94, v112, v113
	v_add_f32_e32 v95, v114, v115
	ds_bpermute_b32 v142, v249, v135
	ds_bpermute_b32 v143, v250, v135
	s_waitcnt vmcnt(16)
	v_cvt_pk_f32_fp8_e32 v[104:105], v32
	v_cvt_pk_f32_fp8_e32 v[108:109], v36
	v_cvt_pk_f32_fp8_sdwa v[106:107], v32 src0_sel:WORD_1
	v_cvt_pk_f32_fp8_sdwa v[110:111], v36 src0_sel:WORD_1
	v_pk_mul_f32 v[112:113], v[64:65], v[104:105]
	v_pk_mul_f32 v[114:115], v[64:65], v[108:109]
	v_pk_fma_f32 v[112:113], v[66:67], v[106:107], v[112:113]
	v_pk_fma_f32 v[114:115], v[66:67], v[110:111], v[114:115]
	v_cvt_pk_f32_fp8_e32 v[104:105], v33
	v_cvt_pk_f32_fp8_e32 v[108:109], v37
	v_cvt_pk_f32_fp8_sdwa v[106:107], v33 src0_sel:WORD_1
	v_cvt_pk_f32_fp8_sdwa v[110:111], v37 src0_sel:WORD_1
	v_pk_fma_f32 v[112:113], v[68:69], v[104:105], v[112:113]
	v_pk_fma_f32 v[114:115], v[68:69], v[108:109], v[114:115]
	v_pk_fma_f32 v[112:113], v[70:71], v[106:107], v[112:113]
	v_pk_fma_f32 v[114:115], v[70:71], v[110:111], v[114:115]
	v_cvt_pk_f32_fp8_e32 v[104:105], v34
	v_cvt_pk_f32_fp8_e32 v[108:109], v38
	v_cvt_pk_f32_fp8_sdwa v[106:107], v34 src0_sel:WORD_1
	v_cvt_pk_f32_fp8_sdwa v[110:111], v38 src0_sel:WORD_1
	v_pk_fma_f32 v[112:113], v[72:73], v[104:105], v[112:113]
	v_pk_fma_f32 v[114:115], v[72:73], v[108:109], v[114:115]
	v_pk_fma_f32 v[112:113], v[74:75], v[106:107], v[112:113]
	v_pk_fma_f32 v[114:115], v[74:75], v[110:111], v[114:115]
	v_cvt_pk_f32_fp8_e32 v[104:105], v35
	v_cvt_pk_f32_fp8_e32 v[108:109], v39
	v_cvt_pk_f32_fp8_sdwa v[106:107], v35 src0_sel:WORD_1
	v_cvt_pk_f32_fp8_sdwa v[110:111], v39 src0_sel:WORD_1
	v_pk_fma_f32 v[112:113], v[76:77], v[104:105], v[112:113]
	v_pk_fma_f32 v[114:115], v[76:77], v[108:109], v[114:115]
	s_waitcnt lgkmcnt(0)
	v_and_or_b32 v142, v142, s90, v240
	v_and_or_b32 v143, v143, s90, v240
	global_load_dwordx4 v[32:35], v142, s[80:81]
	global_load_dwordx4 v[36:39], v143, s[80:81]
	v_pk_fma_f32 v[112:113], v[78:79], v[106:107], v[112:113]
	v_pk_fma_f32 v[114:115], v[78:79], v[110:111], v[114:115]
	v_add_f32_e32 v96, v112, v113
	v_add_f32_e32 v97, v114, v115
	ds_bpermute_b32 v142, v251, v135
	ds_bpermute_b32 v143, v252, v135
	s_waitcnt vmcnt(16)
	v_cvt_pk_f32_fp8_e32 v[104:105], v40
	v_cvt_pk_f32_fp8_e32 v[108:109], v44
	v_cvt_pk_f32_fp8_sdwa v[106:107], v40 src0_sel:WORD_1
	v_cvt_pk_f32_fp8_sdwa v[110:111], v44 src0_sel:WORD_1
	v_pk_mul_f32 v[112:113], v[64:65], v[104:105]
	v_pk_mul_f32 v[114:115], v[64:65], v[108:109]
	v_pk_fma_f32 v[112:113], v[66:67], v[106:107], v[112:113]
	v_pk_fma_f32 v[114:115], v[66:67], v[110:111], v[114:115]
	v_cvt_pk_f32_fp8_e32 v[104:105], v41
	v_cvt_pk_f32_fp8_e32 v[108:109], v45
	v_cvt_pk_f32_fp8_sdwa v[106:107], v41 src0_sel:WORD_1
	v_cvt_pk_f32_fp8_sdwa v[110:111], v45 src0_sel:WORD_1
	v_pk_fma_f32 v[112:113], v[68:69], v[104:105], v[112:113]
	v_pk_fma_f32 v[114:115], v[68:69], v[108:109], v[114:115]
	v_pk_fma_f32 v[112:113], v[70:71], v[106:107], v[112:113]
	v_pk_fma_f32 v[114:115], v[70:71], v[110:111], v[114:115]
	v_cvt_pk_f32_fp8_e32 v[104:105], v42
	v_cvt_pk_f32_fp8_e32 v[108:109], v46
	v_cvt_pk_f32_fp8_sdwa v[106:107], v42 src0_sel:WORD_1
	v_cvt_pk_f32_fp8_sdwa v[110:111], v46 src0_sel:WORD_1
	v_pk_fma_f32 v[112:113], v[72:73], v[104:105], v[112:113]
	v_pk_fma_f32 v[114:115], v[72:73], v[108:109], v[114:115]
	v_pk_fma_f32 v[112:113], v[74:75], v[106:107], v[112:113]
	v_pk_fma_f32 v[114:115], v[74:75], v[110:111], v[114:115]
	v_cvt_pk_f32_fp8_e32 v[104:105], v43
	v_cvt_pk_f32_fp8_e32 v[108:109], v47
	v_cvt_pk_f32_fp8_sdwa v[106:107], v43 src0_sel:WORD_1
	v_cvt_pk_f32_fp8_sdwa v[110:111], v47 src0_sel:WORD_1
	v_pk_fma_f32 v[112:113], v[76:77], v[104:105], v[112:113]
	v_pk_fma_f32 v[114:115], v[76:77], v[108:109], v[114:115]
	s_waitcnt lgkmcnt(0)
	v_and_or_b32 v142, v142, s90, v240
	v_and_or_b32 v143, v143, s90, v240
	global_load_dwordx4 v[40:43], v142, s[80:81]
	global_load_dwordx4 v[44:47], v143, s[80:81]
	v_pk_fma_f32 v[112:113], v[78:79], v[106:107], v[112:113]
	v_pk_fma_f32 v[114:115], v[78:79], v[110:111], v[114:115]
	v_add_f32_e32 v98, v112, v113
	v_add_f32_e32 v99, v114, v115
	ds_bpermute_b32 v142, v253, v135
	ds_bpermute_b32 v143, v254, v135
	s_waitcnt vmcnt(16)
	v_cvt_pk_f32_fp8_e32 v[104:105], v48
	v_cvt_pk_f32_fp8_e32 v[108:109], v52
	v_cvt_pk_f32_fp8_sdwa v[106:107], v48 src0_sel:WORD_1
	v_cvt_pk_f32_fp8_sdwa v[110:111], v52 src0_sel:WORD_1
	v_pk_mul_f32 v[112:113], v[64:65], v[104:105]
	v_pk_mul_f32 v[114:115], v[64:65], v[108:109]
	v_pk_fma_f32 v[112:113], v[66:67], v[106:107], v[112:113]
	v_pk_fma_f32 v[114:115], v[66:67], v[110:111], v[114:115]
	v_cvt_pk_f32_fp8_e32 v[104:105], v49
	v_cvt_pk_f32_fp8_e32 v[108:109], v53
	v_cvt_pk_f32_fp8_sdwa v[106:107], v49 src0_sel:WORD_1
	v_cvt_pk_f32_fp8_sdwa v[110:111], v53 src0_sel:WORD_1
	v_pk_fma_f32 v[112:113], v[68:69], v[104:105], v[112:113]
	v_pk_fma_f32 v[114:115], v[68:69], v[108:109], v[114:115]
	v_pk_fma_f32 v[112:113], v[70:71], v[106:107], v[112:113]
	v_pk_fma_f32 v[114:115], v[70:71], v[110:111], v[114:115]
	v_cvt_pk_f32_fp8_e32 v[104:105], v50
	v_cvt_pk_f32_fp8_e32 v[108:109], v54
	v_cvt_pk_f32_fp8_sdwa v[106:107], v50 src0_sel:WORD_1
	v_cvt_pk_f32_fp8_sdwa v[110:111], v54 src0_sel:WORD_1
	v_pk_fma_f32 v[112:113], v[72:73], v[104:105], v[112:113]
	v_pk_fma_f32 v[114:115], v[72:73], v[108:109], v[114:115]
	v_pk_fma_f32 v[112:113], v[74:75], v[106:107], v[112:113]
	v_pk_fma_f32 v[114:115], v[74:75], v[110:111], v[114:115]
	v_cvt_pk_f32_fp8_e32 v[104:105], v51
	v_cvt_pk_f32_fp8_e32 v[108:109], v55
	v_cvt_pk_f32_fp8_sdwa v[106:107], v51 src0_sel:WORD_1
	v_cvt_pk_f32_fp8_sdwa v[110:111], v55 src0_sel:WORD_1
	v_pk_fma_f32 v[112:113], v[76:77], v[104:105], v[112:113]
	v_pk_fma_f32 v[114:115], v[76:77], v[108:109], v[114:115]
	s_waitcnt lgkmcnt(0)
	v_and_or_b32 v142, v142, s90, v240
	v_and_or_b32 v143, v143, s90, v240
	global_load_dwordx4 v[48:51], v142, s[80:81]
	global_load_dwordx4 v[52:55], v143, s[80:81]
	v_pk_fma_f32 v[112:113], v[78:79], v[106:107], v[112:113]
	v_pk_fma_f32 v[114:115], v[78:79], v[110:111], v[114:115]
	v_add_f32_e32 v100, v112, v113
	v_add_f32_e32 v101, v114, v115
	ds_bpermute_b32 v142, v255, v135
	ds_bpermute_b32 v143, v153, v135
	s_waitcnt vmcnt(16)
	v_cvt_pk_f32_fp8_e32 v[104:105], v56
	v_cvt_pk_f32_fp8_e32 v[108:109], v60
	v_cvt_pk_f32_fp8_sdwa v[106:107], v56 src0_sel:WORD_1
	v_cvt_pk_f32_fp8_sdwa v[110:111], v60 src0_sel:WORD_1
	v_pk_mul_f32 v[112:113], v[64:65], v[104:105]
	v_pk_mul_f32 v[114:115], v[64:65], v[108:109]
	v_pk_fma_f32 v[112:113], v[66:67], v[106:107], v[112:113]
	v_pk_fma_f32 v[114:115], v[66:67], v[110:111], v[114:115]
	v_cvt_pk_f32_fp8_e32 v[104:105], v57
	v_cvt_pk_f32_fp8_e32 v[108:109], v61
	v_cvt_pk_f32_fp8_sdwa v[106:107], v57 src0_sel:WORD_1
	v_cvt_pk_f32_fp8_sdwa v[110:111], v61 src0_sel:WORD_1
	v_pk_fma_f32 v[112:113], v[68:69], v[104:105], v[112:113]
	v_pk_fma_f32 v[114:115], v[68:69], v[108:109], v[114:115]
	v_pk_fma_f32 v[112:113], v[70:71], v[106:107], v[112:113]
	v_pk_fma_f32 v[114:115], v[70:71], v[110:111], v[114:115]
	v_cvt_pk_f32_fp8_e32 v[104:105], v58
	v_cvt_pk_f32_fp8_e32 v[108:109], v62
	v_cvt_pk_f32_fp8_sdwa v[106:107], v58 src0_sel:WORD_1
	v_cvt_pk_f32_fp8_sdwa v[110:111], v62 src0_sel:WORD_1
	v_pk_fma_f32 v[112:113], v[72:73], v[104:105], v[112:113]
	v_pk_fma_f32 v[114:115], v[72:73], v[108:109], v[114:115]
	v_pk_fma_f32 v[112:113], v[74:75], v[106:107], v[112:113]
	v_pk_fma_f32 v[114:115], v[74:75], v[110:111], v[114:115]
	v_cvt_pk_f32_fp8_e32 v[104:105], v59
	v_cvt_pk_f32_fp8_e32 v[108:109], v63
	v_cvt_pk_f32_fp8_sdwa v[106:107], v59 src0_sel:WORD_1
	v_cvt_pk_f32_fp8_sdwa v[110:111], v63 src0_sel:WORD_1
	v_pk_fma_f32 v[112:113], v[76:77], v[104:105], v[112:113]
	v_pk_fma_f32 v[114:115], v[76:77], v[108:109], v[114:115]
	s_waitcnt lgkmcnt(0)
	v_and_or_b32 v142, v142, s90, v240
	v_and_or_b32 v143, v143, s90, v240
	global_load_dwordx4 v[56:59], v142, s[80:81]
	global_load_dwordx4 v[60:63], v143, s[80:81]
	v_pk_fma_f32 v[112:113], v[78:79], v[106:107], v[112:113]
	v_pk_fma_f32 v[114:115], v[78:79], v[110:111], v[114:115]
	v_add_f32_e32 v102, v112, v113
	v_add_f32_e32 v103, v114, v115
	s_add_u32 s92, s100, 2
	s_min_u32 s92, s92, 127
	s_and_b32 s92, s92, 15
	s_lshl_b32 vcc_lo, s92, 9
	s_add_u32 vcc_lo, vcc_lo, s101
	v_add_u32_e32 v116, vcc_lo, v234
	ds_read_b32 v134, v116
	ds_read_b32 v135, v116 offset:256
	s_lshl_b32 vcc_lo, s98, 9
	s_add_u32 vcc_lo, vcc_lo, s101
	s_add_u32 vcc_lo, vcc_lo, 0x10000
	v_add_u32_e32 v117, vcc_lo, v234
	ds_read_b32 v136, v117
	ds_read_b32 v137, v117 offset:256
	s_mov_b32 s88, 0xf0f0f0f0
	s_mov_b32 s89, 0xf0f0f0f0
	v_cndmask_b32_e64 v144, v88, v92, s[88:89]
	v_cndmask_b32_e64 v92, v92, v88, s[88:89]
	v_cndmask_b32_e64 v145, v89, v93, s[88:89]
	v_cndmask_b32_e64 v93, v93, v89, s[88:89]
	v_cndmask_b32_e64 v146, v90, v94, s[88:89]
	v_cndmask_b32_e64 v94, v94, v90, s[88:89]
	v_cndmask_b32_e64 v147, v91, v95, s[88:89]
	v_cndmask_b32_e64 v95, v95, v91, s[88:89]
	v_add_f32_dpp v88, v92, v144 row_half_mirror row_mask:0xf bank_mask:0xf
	v_add_f32_dpp v89, v93, v145 row_half_mirror row_mask:0xf bank_mask:0xf
	v_add_f32_dpp v90, v94, v146 row_half_mirror row_mask:0xf bank_mask:0xf
	v_add_f32_dpp v91, v95, v147 row_half_mirror row_mask:0xf bank_mask:0xf
	v_cndmask_b32_e64 v144, v96, v100, s[88:89]
	v_cndmask_b32_e64 v100, v100, v96, s[88:89]
	v_cndmask_b32_e64 v145, v97, v101, s[88:89]
	v_cndmask_b32_e64 v101, v101, v97, s[88:89]
	v_cndmask_b32_e64 v146, v98, v102, s[88:89]
	v_cndmask_b32_e64 v102, v102, v98, s[88:89]
	v_cndmask_b32_e64 v147, v99, v103, s[88:89]
	v_cndmask_b32_e64 v103, v103, v99, s[88:89]
	v_add_f32_dpp v96, v100, v144 row_half_mirror row_mask:0xf bank_mask:0xf
	v_add_f32_dpp v97, v101, v145 row_half_mirror row_mask:0xf bank_mask:0xf
	v_add_f32_dpp v98, v102, v146 row_half_mirror row_mask:0xf bank_mask:0xf
	v_add_f32_dpp v99, v103, v147 row_half_mirror row_mask:0xf bank_mask:0xf
	s_mov_b32 s88, 0xcccccccc
	s_mov_b32 s89, 0xcccccccc
	v_cndmask_b32_e64 v144, v88, v90, s[88:89]
	v_cndmask_b32_e64 v90, v90, v88, s[88:89]
	v_cndmask_b32_e64 v145, v89, v91, s[88:89]
	v_cndmask_b32_e64 v91, v91, v89, s[88:89]
	v_cndmask_b32_e64 v146, v96, v98, s[88:89]
	v_cndmask_b32_e64 v98, v98, v96, s[88:89]
	v_cndmask_b32_e64 v147, v97, v99, s[88:89]
	v_cndmask_b32_e64 v99, v99, v97, s[88:89]
	v_add_f32_dpp v88, v90, v144 quad_perm:[2,3,0,1] row_mask:0xf bank_mask:0xf
	v_add_f32_dpp v89, v91, v145 quad_perm:[2,3,0,1] row_mask:0xf bank_mask:0xf
	v_add_f32_dpp v96, v98, v146 quad_perm:[2,3,0,1] row_mask:0xf bank_mask:0xf
	v_add_f32_dpp v97, v99, v147 quad_perm:[2,3,0,1] row_mask:0xf bank_mask:0xf
	s_mov_b32 s88, 0xaaaaaaaa
	s_mov_b32 s89, 0xaaaaaaaa
	v_cndmask_b32_e64 v144, v88, v89, s[88:89]
	v_cndmask_b32_e64 v89, v89, v88, s[88:89]
	v_cndmask_b32_e64 v145, v96, v97, s[88:89]
	v_cndmask_b32_e64 v97, v97, v96, s[88:89]
	s_nop 1
	v_add_f32_dpp v88, v89, v144 quad_perm:[1,0,3,2] row_mask:0xf bank_mask:0xf
	v_add_f32_dpp v96, v97, v145 quad_perm:[1,0,3,2] row_mask:0xf bank_mask:0xf
	s_nop 0
	ds_bpermute_b32 v144, v239, v88
	ds_bpermute_b32 v145, v239, v96
	s_waitcnt lgkmcnt(0)
	v_add_f32_e32 v136, v136, v144
	v_add_f32_e32 v137, v137, v145
	ds_write_b32 v117, v136
	ds_write_b32 v117, v137 offset:256
	s_add_u32 s100, s100, 1
	s_cmp_lt_u32 s100, 128
	s_cbranch_scc1 .Lpg1_uloop
	s_waitcnt vmcnt(0) lgkmcnt(0)
	s_mov_b32 s2, 0

; DEV unsigned pk2(float lo, float hi) { f32x2_t v = {lo, hi}; bf16x2_t b = __builtin_convertvector(v, bf16x2_t); return __builtin_bit_cast(unsigned, b); }
; DEV void peer_gather(const Params& P, int l, int m0, const int* idxs, const float* gs) {
;     ...
;     const float rstd = rsqrtf(wave_sum(ss) * (1.f / DM) + EPS);
;     u32x4 oa, ob;
; #pragma unroll
;     for (int q = 0; q < 4; ++q) {
;       const f32x4 g = *(const f32x4*)(gp + lane * 16 + 4 * q);
;       const unsigned p0 = pk2(hv[q][0] * rstd * g[0], hv[q][1] * rstd * g[1]), p1 = pk2(hv[q][2] * rstd * g[2], hv[q][3] * rstd * g[3]);
;       if (q < 2) { oa[2 * q] = p0; oa[2 * q + 1] = p1; } else { ob[2 * (q - 2)] = p0; ob[2 * (q - 2) + 1] = p1; }
;     }
;     *(u32x4*)(hn + tok * DM + lane * 16) = oa; *(u32x4*)(hn + tok * DM + lane * 16 + 8) = ob;
.Lpg1_epi:
	v_readfirstlane_b32 s82, v132
	v_readfirstlane_b32 s83, v133
	s_nop 4
	v_readfirstlane_b32 s84, v122
	v_readfirstlane_b32 s85, v123
	s_nop 4
	s_add_u32 s98, s3, s2
	s_lshl_b32 vcc_lo, s98, 12
	v_lshl_add_u32 v116, v233, 6, vcc_lo
	global_load_dwordx4 v[0:3], v116, s[82:83] offset:0
	global_load_dwordx4 v[4:7], v116, s[82:83] offset:16
	global_load_dwordx4 v[8:11], v116, s[82:83] offset:32
	global_load_dwordx4 v[12:15], v116, s[82:83] offset:48
	s_add_u32 s99, s3, s2
	s_add_u32 s99, s99, 1
	s_lshl_b32 vcc_lo, s99, 12
	v_lshl_add_u32 v149, v233, 6, vcc_lo
	global_load_dwordx4 v[32:35], v149, s[82:83] offset:0
	global_load_dwordx4 v[36:39], v149, s[82:83] offset:16
	global_load_dwordx4 v[40:43], v149, s[82:83] offset:32
	global_load_dwordx4 v[44:47], v149, s[82:83] offset:48
	s_waitcnt vmcnt(4)
	v_pk_mul_f32 v[104:105], v[0:1], v[0:1]
	v_pk_fma_f32 v[104:105], v[2:3], v[2:3], v[104:105]
	v_pk_fma_f32 v[104:105], v[4:5], v[4:5], v[104:105]
	v_pk_fma_f32 v[104:105], v[6:7], v[6:7], v[104:105]
	v_pk_fma_f32 v[104:105], v[8:9], v[8:9], v[104:105]
	v_pk_fma_f32 v[104:105], v[10:11], v[10:11], v[104:105]
	v_pk_fma_f32 v[104:105], v[12:13], v[12:13], v[104:105]
	v_pk_fma_f32 v[104:105], v[14:15], v[14:15], v[104:105]
	v_add_f32_e32 v118, v104, v105
	s_nop 1
	v_add_f32_dpp v118, v118, v118 quad_perm:[1,0,3,2] row_mask:0xf bank_mask:0xf
	s_nop 1
	v_add_f32_dpp v118, v118, v118 quad_perm:[2,3,0,1] row_mask:0xf bank_mask:0xf
	s_nop 1
	v_add_f32_dpp v118, v118, v118 row_half_mirror row_mask:0xf bank_mask:0xf
	s_nop 1
	v_add_f32_dpp v118, v118, v118 row_mirror row_mask:0xf bank_mask:0xf
	v_xor_b32_e32 v119, 64, v234
	ds_bpermute_b32 v119, v119, v118
	s_waitcnt lgkmcnt(0)
	v_add_f32_e32 v118, v118, v119
	v_xor_b32_e32 v119, 128, v234
	ds_bpermute_b32 v119, v119, v118
	s_waitcnt lgkmcnt(0)
	v_add_f32_e32 v118, v118, v119
	v_mov_b32_e32 v119, 0x358637bd
	v_fmac_f32_e32 v119, 0x3a800000, v118
	v_rsq_f32_e32 v106, v119
	s_nop 1
	v_pk_mul_f32 v[0:1], v[0:1], v[106:107] op_sel_hi:[1,0]
	v_pk_mul_f32 v[2:3], v[2:3], v[106:107] op_sel_hi:[1,0]
	v_pk_mul_f32 v[4:5], v[4:5], v[106:107] op_sel_hi:[1,0]
	v_pk_mul_f32 v[6:7], v[6:7], v[106:107] op_sel_hi:[1,0]
	v_pk_mul_f32 v[8:9], v[8:9], v[106:107] op_sel_hi:[1,0]
	v_pk_mul_f32 v[10:11], v[10:11], v[106:107] op_sel_hi:[1,0]
	v_pk_mul_f32 v[12:13], v[12:13], v[106:107] op_sel_hi:[1,0]
	v_pk_mul_f32 v[14:15], v[14:15], v[106:107] op_sel_hi:[1,0]
	v_pk_mul_f32 v[0:1], v[16:17], v[0:1]
	v_pk_mul_f32 v[2:3], v[18:19], v[2:3]
	v_pk_mul_f32 v[4:5], v[20:21], v[4:5]
	v_pk_mul_f32 v[6:7], v[22:23], v[6:7]
	v_pk_mul_f32 v[8:9], v[24:25], v[8:9]
	v_pk_mul_f32 v[10:11], v[26:27], v[10:11]
	v_pk_mul_f32 v[12:13], v[28:29], v[12:13]
	v_pk_mul_f32 v[14:15], v[30:31], v[14:15]
	v_cvt_pk_bf16_f32 v48, v0, v1
	v_cvt_pk_bf16_f32 v49, v2, v3
	v_cvt_pk_bf16_f32 v50, v4, v5
	v_cvt_pk_bf16_f32 v51, v6, v7
	v_cvt_pk_bf16_f32 v52, v8, v9
	v_cvt_pk_bf16_f32 v53, v10, v11
	v_cvt_pk_bf16_f32 v54, v12, v13
	v_cvt_pk_bf16_f32 v55, v14, v15
	s_lshl_b32 vcc_lo, s98, 11
	v_lshl_add_u32 v116, v233, 5, vcc_lo
	global_store_dwordx4 v116, v[48:51], s[84:85]
	global_store_dwordx4 v116, v[52:55], s[84:85] offset:16
	s_waitcnt vmcnt(2)
	v_pk_mul_f32 v[104:105], v[32:33], v[32:33]
	v_pk_fma_f32 v[104:105], v[34:35], v[34:35], v[104:105]
	v_pk_fma_f32 v[104:105], v[36:37], v[36:37], v[104:105]
	v_pk_fma_f32 v[104:105], v[38:39], v[38:39], v[104:105]
	v_pk_fma_f32 v[104:105], v[40:41], v[40:41], v[104:105]
	v_pk_fma_f32 v[104:105], v[42:43], v[42:43], v[104:105]
	v_pk_fma_f32 v[104:105], v[44:45], v[44:45], v[104:105]
	v_pk_fma_f32 v[104:105], v[46:47], v[46:47], v[104:105]
	v_add_f32_e32 v118, v104, v105
	s_nop 1
	v_add_f32_dpp v118, v118, v118 quad_perm:[1,0,3,2] row_mask:0xf bank_mask:0xf
	s_nop 1
	v_add_f32_dpp v118, v118, v118 quad_perm:[2,3,0,1] row_mask:0xf bank_mask:0xf
	s_nop 1
	v_add_f32_dpp v118, v118, v118 row_half_mirror row_mask:0xf bank_mask:0xf
	s_nop 1
	v_add_f32_dpp v118, v118, v118 row_mirror row_mask:0xf bank_mask:0xf
	v_xor_b32_e32 v119, 64, v234
	ds_bpermute_b32 v119, v119, v118
	s_waitcnt lgkmcnt(0)
	v_add_f32_e32 v118, v118, v119
	v_xor_b32_e32 v119, 128, v234
	ds_bpermute_b32 v119, v119, v118
	s_waitcnt lgkmcnt(0)
	v_add_f32_e32 v118, v118, v119
	v_mov_b32_e32 v119, 0x358637bd
	v_fmac_f32_e32 v119, 0x3a800000, v118
	v_rsq_f32_e32 v106, v119
	s_nop 1
	v_pk_mul_f32 v[32:33], v[32:33], v[106:107] op_sel_hi:[1,0]
	v_pk_mul_f32 v[34:35], v[34:35], v[106:107] op_sel_hi:[1,0]
	v_pk_mul_f32 v[36:37], v[36:37], v[106:107] op_sel_hi:[1,0]
	v_pk_mul_f32 v[38:39], v[38:39], v[106:107] op_sel_hi:[1,0]
	v_pk_mul_f32 v[40:41], v[40:41], v[106:107] op_sel_hi:[1,0]
	v_pk_mul_f32 v[42:43], v[42:43], v[106:107] op_sel_hi:[1,0]
	v_pk_mul_f32 v[44:45], v[44:45], v[106:107] op_sel_hi:[1,0]
	v_pk_mul_f32 v[46:47], v[46:47], v[106:107] op_sel_hi:[1,0]
	v_pk_mul_f32 v[32:33], v[16:17], v[32:33]
	v_pk_mul_f32 v[34:35], v[18:19], v[34:35]
	v_pk_mul_f32 v[36:37], v[20:21], v[36:37]
	v_pk_mul_f32 v[38:39], v[22:23], v[38:39]
	v_pk_mul_f32 v[40:41], v[24:25], v[40:41]
	v_pk_mul_f32 v[42:43], v[26:27], v[42:43]
	v_pk_mul_f32 v[44:45], v[28:29], v[44:45]
	v_pk_mul_f32 v[46:47], v[30:31], v[46:47]
	v_cvt_pk_bf16_f32 v48, v32, v33
	v_cvt_pk_bf16_f32 v49, v34, v35
	v_cvt_pk_bf16_f32 v50, v36, v37
	v_cvt_pk_bf16_f32 v51, v38, v39
	v_cvt_pk_bf16_f32 v52, v40, v41
	v_cvt_pk_bf16_f32 v53, v42, v43
	v_cvt_pk_bf16_f32 v54, v44, v45
	v_cvt_pk_bf16_f32 v55, v46, v47
	s_lshl_b32 vcc_lo, s99, 11
	v_lshl_add_u32 v149, v233, 5, vcc_lo
	global_store_dwordx4 v149, v[48:51], s[84:85]
	global_store_dwordx4 v149, v[52:55], s[84:85] offset:16
	s_add_u32 s2, s2, 2
	s_cmp_lt_u32 s2, 16
	s_cbranch_scc1 .Lpg1_epi
	s_waitcnt vmcnt(0) lgkmcnt(0)
	v_readlane_b32 s92, v231, 15
	v_readlane_b32 s93, v231, 16
